# v29 plus attention s_setprio 0 moved behind the segment-closing barrier (role-split attention loop)
# baseline (speedup 1.0000x reference)
; #define SBAR() __builtin_amdgcn_sched_barrier(0)
; #define QKT(P0, P1, KS) do { if (MODE == 1) qkt_lds(P0, P1, KS, qs, r32, hi); else qkt(P0, P1, KS, qr, r32, hi); } while (0)
; __device__ __forceinline__ void finishSM(f32x16& p0, f32x16& p1, float alpha, float& l_reg, bf16x8& pa0, bf16x8& pa1, bf16x8& pa2, bf16x8& pa3) {
;   for (int r = 0; r < 16; ++r) p1[r] = __builtin_amdgcn_exp2f(p1[r]);
;   float ps = 0; for (int r = 0; r < 16; ++r) ps += p0[r]; for (int r = 0; r < 16; ++r) ps += p1[r];
;   { auto rr = __builtin_amdgcn_permlane32_swap(__float_as_uint(ps), __float_as_uint(ps), false, false);
;     ps = __uint_as_float(rr[0]) + __uint_as_float(rr[1]); }
;   l_reg = l_reg * alpha + ps;
;     ...
;   PK4(p0, 0, pa0); PK4(p0, 8, pa1); PK4(p1, 0, pa2); PK4(p1, 8, pa3);
;     ...
; }
; __device__ __forceinline__ void qkt(f32x16& p0, f32x16& p1, const u16* Ks, const bf16x8* qr, int r32, int hi) {
;   p0 = f32x16{}; p1 = f32x16{};
;   for (int d0 = 0; d0 < 8; ++d0) { int cb = (d0 * 16 + hi * 8) * 2;
;     bf16x8 b0 = *reinterpret_cast<const bf16x8*>((const char*)Ks + KSWZ(r32, cb));
;     bf16x8 b1 = *reinterpret_cast<const bf16x8*>((const char*)Ks + KSWZ(32 + r32, cb));
;     p0 = __builtin_amdgcn_mfma_f32_32x32x16_bf16(b0, qr[d0], p0, 0, 0, 0);
;     p1 = __builtin_amdgcn_mfma_f32_32x32x16_bf16(b1, qr[d0], p1, 0, 0, 0); }
; }
; template <int MODE> ...
;     ...
;     for (int j = 1; j + 1 < NT; j += 2) {
;       const int s0_ = sj, s1_ = sj == 2 ? 0 : sj + 1, s2_ = s1_ == 2 ? 0 : s1_ + 1;
;       SBAR(); QKT(pB0, pB1, (u16*)((char*)K_lds + s0_ * SHM_K));
;       finishSM(pA0, pA1, alA, l_reg, pa0, pa1, pa2, pa3); SBAR();
;       { const int tn = (j + 2 < NT) ? j + 2 : NT - 1; SLOAD(SO, tn); } SBAR();
.LBB0_474:
	s_add_i32 s7, s89, 1
	s_cmp_lg_u32 s89, 2
	s_cselect_b32 s66, s7, 0
	s_add_i32 s7, s66, 1
	s_cmp_lg_u32 s66, 2
	s_mov_b32 s6, s89
	s_cselect_b32 s89, s7, 0
	s_lshl_b32 s93, s6, 14
	s_add_i32 s6, s93, 0
	s_setprio 1
	v_add_u32_e32 v254, s6, v189
	ds_read_b128 v[68:71], v254 offset:49152
	ds_read_b128 v[72:75], v254 offset:49280
	v_add_u32_e32 v254, s6, v190
	ds_read_b128 v[76:79], v254 offset:49152
	ds_read_b128 v[80:83], v254 offset:49280
	v_add_u32_e32 v254, s6, v191
	ds_read_b128 v[220:223], v254 offset:49152
	ds_read_b128 v[224:227], v254 offset:49280
	v_add_u32_e32 v254, s6, v192
	ds_read_b128 v[228:231], v254 offset:49152
	ds_read_b128 v[232:235], v254 offset:49280
	v_add_u32_e32 v254, s6, v189
	ds_read_b128 v[236:239], v254 offset:57344
	ds_read_b128 v[240:243], v254 offset:57472
	s_waitcnt lgkmcnt(9)
	v_mfma_f32_32x32x16_bf16 v[84:99], v[68:71], v[100:103], 0
	s_waitcnt lgkmcnt(8)
	v_mfma_f32_32x32x16_bf16 v[84:99], v[72:75], v[116:119], v[84:99]
	s_waitcnt lgkmcnt(7)
	v_mfma_f32_32x32x16_bf16 v[84:99], v[76:79], v[104:107], v[84:99]
	s_waitcnt lgkmcnt(6)
	v_mfma_f32_32x32x16_bf16 v[84:99], v[80:83], v[120:123], v[84:99]
	s_waitcnt lgkmcnt(5)
	v_mfma_f32_32x32x16_bf16 v[84:99], v[220:223], v[108:111], v[84:99]
	v_add_u32_e32 v254, s6, v190
	ds_read_b128 v[220:223], v254 offset:57344
	s_waitcnt lgkmcnt(5)
	v_mfma_f32_32x32x16_bf16 v[84:99], v[224:227], v[124:127], v[84:99]
	ds_read_b128 v[224:227], v254 offset:57472
	s_waitcnt lgkmcnt(5)
	v_mfma_f32_32x32x16_bf16 v[84:99], v[228:231], v[112:115], v[84:99]
	v_add_u32_e32 v254, s6, v191
	ds_read_b128 v[228:231], v254 offset:57344
	s_waitcnt lgkmcnt(5)
	v_mfma_f32_32x32x16_bf16 v[84:99], v[232:235], v[128:131], v[84:99]
	ds_read_b128 v[232:235], v254 offset:57472
	s_waitcnt lgkmcnt(5)
	v_mfma_f32_32x32x16_bf16 v[68:83], v[236:239], v[100:103], 0
	v_add_u32_e32 v254, s6, v192
	ds_read_b128 v[236:239], v254 offset:57344
	s_waitcnt lgkmcnt(5)
	v_mfma_f32_32x32x16_bf16 v[68:83], v[240:243], v[116:119], v[68:83]
	ds_read_b128 v[240:243], v254 offset:57472
	s_waitcnt lgkmcnt(5)
	v_mfma_f32_32x32x16_bf16 v[68:83], v[220:223], v[104:107], v[68:83]
	s_waitcnt lgkmcnt(4)
	v_mfma_f32_32x32x16_bf16 v[68:83], v[224:227], v[120:123], v[68:83]
	s_waitcnt lgkmcnt(3)
	v_mfma_f32_32x32x16_bf16 v[68:83], v[228:231], v[108:111], v[68:83]
	s_waitcnt lgkmcnt(2)
	v_mfma_f32_32x32x16_bf16 v[68:83], v[232:235], v[124:127], v[68:83]
	s_waitcnt lgkmcnt(1)
	v_mfma_f32_32x32x16_bf16 v[68:83], v[236:239], v[112:115], v[68:83]
	s_waitcnt lgkmcnt(0)
	v_mfma_f32_32x32x16_bf16 v[68:83], v[240:243], v[128:131], v[68:83]
	s_barrier
	s_setprio 0
	v_exp_f32_e32 v160, v160
	v_exp_f32_e32 v161, v161
	v_exp_f32_e32 v158, v158
	v_exp_f32_e32 v159, v159
	v_exp_f32_e32 v156, v156
	v_exp_f32_e32 v157, v157
	v_exp_f32_e32 v154, v154
	v_exp_f32_e32 v155, v155
	v_exp_f32_e32 v152, v152
	v_exp_f32_e32 v153, v153
	v_exp_f32_e32 v150, v150
	v_exp_f32_e32 v151, v151
	v_exp_f32_e32 v148, v148
	v_exp_f32_e32 v149, v149
	v_exp_f32_e32 v2, v162
	v_exp_f32_e32 v162, v163
	v_add_f32_e32 v163, 0, v216
	v_add_f32_e32 v163, v218, v163
	v_add_f32_e32 v163, v214, v163
	v_add_f32_e32 v163, v217, v163
	v_add_f32_e32 v163, v213, v163
	v_add_f32_e32 v163, v215, v163
	v_add_f32_e32 v163, v211, v163
	v_add_f32_e32 v163, v212, v163
	v_add_f32_e32 v163, v208, v163
	v_add_f32_e32 v163, v210, v163
	v_add_f32_e32 v163, v207, v163
	v_add_f32_e32 v163, v209, v163
	v_add_f32_e32 v163, v204, v163
	v_add_f32_e32 v163, v206, v163
	v_add_f32_e32 v163, v203, v163
	v_add_f32_e32 v163, v205, v163
	v_add_f32_e32 v163, v2, v163
	v_add_f32_e32 v163, v162, v163
	v_add_f32_e32 v163, v160, v163
	v_add_f32_e32 v163, v161, v163
	v_add_f32_e32 v163, v158, v163
	v_add_f32_e32 v163, v159, v163
	v_add_f32_e32 v163, v156, v163
	v_add_f32_e32 v163, v157, v163
	v_add_f32_e32 v163, v154, v163
	v_add_f32_e32 v163, v155, v163
	v_add_f32_e32 v163, v152, v163
	v_add_f32_e32 v163, v153, v163
	v_add_f32_e32 v163, v150, v163
	v_add_f32_e32 v163, v151, v163
	v_add_f32_e32 v163, v148, v163
	v_add_f32_e32 v200, v149, v163
	v_mov_b32_e32 v201, v200
	v_cvt_pk_bf16_f32 v216, v216, v218
	v_cvt_pk_bf16_f32 v217, v214, v217
	v_cvt_pk_bf16_f32 v218, v213, v215
	v_cvt_pk_bf16_f32 v219, v211, v212
	v_cvt_pk_bf16_f32 v208, v208, v210
	v_cvt_pk_bf16_f32 v209, v207, v209
	v_cvt_pk_bf16_f32 v210, v204, v206
	v_cvt_pk_bf16_f32 v211, v203, v205
	v_cvt_pk_bf16_f32 v202, v2, v162
	v_cvt_pk_bf16_f32 v203, v160, v161
	v_cvt_pk_bf16_f32 v204, v158, v159
	v_permlane32_swap_b32_e32 v200, v201
	v_cvt_pk_bf16_f32 v205, v156, v157
	v_permlane32_swap_b32_e32 v202, v204
	v_cvt_pk_bf16_f32 v212, v154, v155
	v_cvt_pk_bf16_f32 v213, v152, v153
	v_cvt_pk_bf16_f32 v214, v150, v151
	v_cvt_pk_bf16_f32 v215, v148, v149
	v_permlane32_swap_b32_e32 v216, v218
	v_permlane32_swap_b32_e32 v217, v219
	v_permlane32_swap_b32_e32 v208, v210
	v_permlane32_swap_b32_e32 v209, v211
	v_permlane32_swap_b32_e32 v203, v205
	v_permlane32_swap_b32_e32 v212, v214
	v_permlane32_swap_b32_e32 v213, v215
	s_add_i32 s91, s16, -1
	s_min_u32 s7, s91, s90
	s_add_i32 s7, s7, s88
	s_lshl_b32 s7, s7, 6
	v_add_u32_e32 v244, s7, v167
	v_add_u32_e32 v245, s7, v185
	v_lshl_or_b32 v244, v244, 8, v182
	v_lshl_or_b32 v245, v245, 8, v182
	global_load_dwordx4 v[152:155], v244, s[58:59]
	global_load_dwordx4 v[148:151], v245, s[58:59]
	global_load_dwordx4 v[160:163], v244, s[64:65]
	global_load_dwordx4 v[156:159], v245, s[64:65]
	s_lshl_b32 s94, s89, 14
	v_add_u32_e32 v254, s94, v197
	ds_read_b64_tr_b16 v[220:221], v254 offset:0
	ds_read_b64_tr_b16 v[222:223], v254 offset:2048
	ds_read_b64_tr_b16 v[224:225], v254 offset:4096
	ds_read_b64_tr_b16 v[226:227], v254 offset:6144
	ds_read_b64_tr_b16 v[228:229], v254 offset:8192
	ds_read_b64_tr_b16 v[230:231], v254 offset:10240
	ds_read_b64_tr_b16 v[232:233], v254 offset:12288
	ds_read_b64_tr_b16 v[234:235], v254 offset:14336
	ds_read_b64_tr_b16 v[236:237], v254 offset:512
	ds_read_b64_tr_b16 v[238:239], v254 offset:2560
	s_barrier
; #define SBAR() __builtin_amdgcn_sched_barrier(0)
; __device__ __forceinline__ void partialSM(f32x16& p0, f32x16& p1, float& m_reg, float& mn, float& alpha) {
;   constexpr float C = SCALE * 1.4426950408889634f;
;   float pmax = p0[0]; for (int r = 1; r < 16; ++r) pmax = fmaxf(pmax, p0[r]); for (int r = 0; r < 16; ++r) pmax = fmaxf(pmax, p1[r]);
;   { auto rr = __builtin_amdgcn_permlane32_swap(__float_as_uint(pmax), __float_as_uint(pmax), false, false);
;     pmax = fmaxf(__uint_as_float(rr[0]), __uint_as_float(rr[1])); }
;   if (__builtin_expect(__all(pmax - m_reg <= THR / SCALE), 1)) { mn = m_reg; alpha = 1.f; }
;   else { mn = fmaxf(m_reg, pmax); alpha = __builtin_amdgcn_exp2f((m_reg - mn) * C); m_reg = mn; }
; template <int OFF> __device__ __forceinline__ s16x4 tr_read(int vb) {
;   s16x4 r; asm volatile("ds_read_b64_tr_b16 %0, %1 offset:%2" : "=&v"(r) : "v"(vb), "i"(OFF) : "memory"); return r;
; }
; template <int D0> __device__ __forceinline__ void pv_one(f32x16& od, int vb, bf16x8 pa0, bf16x8 pa1, bf16x8 pa2, bf16x8 pa3) {
;   const s16x4 l0 = tr_read<v_rd_off(D0, 0, 0)>(vb), h0 = tr_read<v_rd_off(D0, 0, 1)>(vb), l1 = tr_read<v_rd_off(D0, 1, 0)>(vb), h1 = tr_read<v_rd_off(D0, 1, 1)>(vb);
;   const s16x4 l2 = tr_read<v_rd_off(D0, 2, 0)>(vb), h2 = tr_read<v_rd_off(D0, 2, 1)>(vb), l3 = tr_read<v_rd_off(D0, 3, 0)>(vb), h3 = tr_read<v_rd_off(D0, 3, 1)>(vb);
;   asm volatile("s_waitcnt lgkmcnt(0)" ::: "memory"); SBAR();
;     ...
;   od = __builtin_amdgcn_mfma_f32_32x32x16_bf16(pa0, PK(l0, h0), od, 0, 0, 0);
;   od = __builtin_amdgcn_mfma_f32_32x32x16_bf16(pa1, PK(l1, h1), od, 0, 0, 0);
;   od = __builtin_amdgcn_mfma_f32_32x32x16_bf16(pa2, PK(l2, h2), od, 0, 0, 0);
;   od = __builtin_amdgcn_mfma_f32_32x32x16_bf16(pa3, PK(l3, h3), od, 0, 0, 0);
;     ...
; }
; __device__ __forceinline__ void pv_d0(f32x16* o, int vb, bf16x8 pa0, bf16x8 pa1, bf16x8 pa2, bf16x8 pa3) {
;   pv_one<0>(o[0], vb, pa0, pa1, pa2, pa3); pv_one<1>(o[1], vb, pa0, pa1, pa2, pa3); pv_one<2>(o[2], vb, pa0, pa1, pa2, pa3); pv_one<3>(o[3], vb, pa0, pa1, pa2, pa3);
	s_setprio 1
	s_waitcnt lgkmcnt(6)
	v_mfma_f32_32x32x16_bf16 v[52:67], v[216:219], v[220:223], v[52:67]
	ds_read_b64_tr_b16 v[240:241], v254 offset:4608
	ds_read_b64_tr_b16 v[242:243], v254 offset:6656
	v_mfma_f32_32x32x16_bf16 v[52:67], v[208:211], v[224:227], v[52:67]
	ds_read_b64_tr_b16 v[220:221], v254 offset:8704
	ds_read_b64_tr_b16 v[222:223], v254 offset:10752
	s_waitcnt lgkmcnt(6)
	v_mfma_f32_32x32x16_bf16 v[52:67], v[202:205], v[228:231], v[52:67]
	ds_read_b64_tr_b16 v[224:225], v254 offset:12800
	ds_read_b64_tr_b16 v[226:227], v254 offset:14848
	v_mfma_f32_32x32x16_bf16 v[52:67], v[212:215], v[232:235], v[52:67]
	ds_read_b64_tr_b16 v[228:229], v254 offset:1024
	ds_read_b64_tr_b16 v[230:231], v254 offset:3072
	s_waitcnt lgkmcnt(6)
	v_mfma_f32_32x32x16_bf16 v[36:51], v[216:219], v[236:239], v[36:51]
	ds_read_b64_tr_b16 v[232:233], v254 offset:5120
	ds_read_b64_tr_b16 v[234:235], v254 offset:7168
	v_mfma_f32_32x32x16_bf16 v[36:51], v[208:211], v[240:243], v[36:51]
	ds_read_b64_tr_b16 v[236:237], v254 offset:9216
	ds_read_b64_tr_b16 v[238:239], v254 offset:11264
	s_waitcnt lgkmcnt(6)
	v_mfma_f32_32x32x16_bf16 v[36:51], v[202:205], v[220:223], v[36:51]
	ds_read_b64_tr_b16 v[240:241], v254 offset:13312
	ds_read_b64_tr_b16 v[242:243], v254 offset:15360
	v_mfma_f32_32x32x16_bf16 v[36:51], v[212:215], v[224:227], v[36:51]
	ds_read_b64_tr_b16 v[220:221], v254 offset:1536
	ds_read_b64_tr_b16 v[222:223], v254 offset:3584
	s_waitcnt lgkmcnt(6)
	v_mfma_f32_32x32x16_bf16 v[20:35], v[216:219], v[228:231], v[20:35]
	ds_read_b64_tr_b16 v[224:225], v254 offset:5632
	ds_read_b64_tr_b16 v[226:227], v254 offset:7680
	v_mfma_f32_32x32x16_bf16 v[20:35], v[208:211], v[232:235], v[20:35]
	ds_read_b64_tr_b16 v[228:229], v254 offset:9728
	ds_read_b64_tr_b16 v[230:231], v254 offset:11776
	s_waitcnt lgkmcnt(6)
	v_mfma_f32_32x32x16_bf16 v[20:35], v[202:205], v[236:239], v[20:35]
	ds_read_b64_tr_b16 v[232:233], v254 offset:13824
	ds_read_b64_tr_b16 v[234:235], v254 offset:15872
	v_mfma_f32_32x32x16_bf16 v[20:35], v[212:215], v[240:243], v[20:35]
	s_waitcnt lgkmcnt(4)
	v_mfma_f32_32x32x16_bf16 v[4:19], v[216:219], v[220:223], v[4:19]
	s_waitcnt vmcnt(4)
	v_mfma_f32_32x32x16_bf16 v[4:19], v[208:211], v[224:227], v[4:19]
	s_waitcnt lgkmcnt(0)
	v_mfma_f32_32x32x16_bf16 v[4:19], v[202:205], v[228:231], v[4:19]
	v_mfma_f32_32x32x16_bf16 v[4:19], v[212:215], v[232:235], v[4:19]
	s_barrier
	s_setprio 0
	s_lshl_b32 s92, s66, 14
	s_add_i32 s95, s92, 0
	v_add_u32_e32 v203, s95, v184
	ds_write_b128 v203, v[136:139]
	v_add_u32_e32 v136, s95, v186
	ds_write_b128 v136, v[132:135]
	v_add_u32_e32 v132, s95, v187
	ds_write_b128 v132, v[144:147] offset:49152
	v_add_u32_e32 v132, s95, v188
	s_waitcnt vmcnt(4)
	ds_write_b128 v132, v[140:143] offset:49152
	v_max_f32_e32 v2, v85, v85
	v_max_f32_e32 v202, v84, v84
	v_max_f32_e32 v2, v202, v2
	v_max3_f32 v2, v2, v86, v87
	v_max3_f32 v2, v2, v88, v89
	v_max3_f32 v2, v2, v90, v91
	v_max3_f32 v2, v2, v92, v93
	v_max3_f32 v2, v2, v94, v95
	v_max3_f32 v2, v2, v96, v97
	v_max3_f32 v2, v2, v98, v99
	v_max3_f32 v2, v2, v68, v69
	v_max3_f32 v2, v2, v70, v71
	v_max3_f32 v2, v2, v72, v73
	v_max3_f32 v2, v2, v74, v75
	v_max3_f32 v2, v2, v76, v77
	v_max3_f32 v2, v2, v78, v79
	v_max3_f32 v2, v2, v80, v81
	v_max3_f32 v2, v2, v82, v83
	v_mov_b32_e32 v202, v2
	s_nop 1
	v_permlane32_swap_b32_e32 v2, v202
	v_max_f32_e32 v202, v202, v202
	v_max_f32_e32 v2, v2, v2
	v_max_f32_e32 v2, v2, v202
	v_sub_f32_e32 v202, v2, v166
	v_cmp_ge_f32_e32 vcc, s74, v202
	v_max_f32_e32 v202, v166, v166
	v_max_f32_e32 v2, v202, v2
	v_sub_f32_e32 v202, v166, v2
	s_cmp_eq_u64 vcc, exec
	v_mul_f32_e32 v202, 0x3e0293ee, v202
	s_cselect_b64 s[6:7], -1, 0
	v_exp_f32_e32 v202, v202
	s_nop 0
	v_cndmask_b32_e64 v202, v202, 1.0, s[6:7]
	v_cmp_gt_f32_e32 vcc, 1.0, v202
	s_cbranch_vccz .LBB0_478
	s_and_saveexec_b64 s[66:67], s[4:5]
	ds_write_b32 v183, v202 offset:128
	s_or_b64 exec, exec, s[66:67]
	s_waitcnt lgkmcnt(0)
	v_add_u32_e32 v144, v181, v180
	ds_read_b128 v[132:135], v144 offset:224
	ds_read_b128 v[136:139], v144 offset:192
	ds_read_b128 v[140:143], v144 offset:160
	ds_read_b128 v[144:147], v144 offset:128
	s_waitcnt lgkmcnt(3)
	v_pk_mul_f32 v[64:65], v[64:65], v[132:133]
	s_waitcnt lgkmcnt(2)
	v_pk_mul_f32 v[60:61], v[60:61], v[136:137]
	s_waitcnt lgkmcnt(1)
	v_pk_mul_f32 v[56:57], v[56:57], v[140:141]
	v_pk_mul_f32 v[66:67], v[66:67], v[134:135]
	v_pk_mul_f32 v[62:63], v[62:63], v[138:139]
	v_pk_mul_f32 v[58:59], v[58:59], v[142:143]
	s_waitcnt lgkmcnt(0)
	v_pk_mul_f32 v[54:55], v[54:55], v[146:147]
	v_pk_mul_f32 v[52:53], v[52:53], v[144:145]
	v_pk_mul_f32 v[48:49], v[48:49], v[132:133]
	v_pk_mul_f32 v[44:45], v[44:45], v[136:137]
	v_pk_mul_f32 v[40:41], v[40:41], v[140:141]
	v_pk_mul_f32 v[50:51], v[50:51], v[134:135]
	v_pk_mul_f32 v[46:47], v[46:47], v[138:139]
	v_pk_mul_f32 v[42:43], v[42:43], v[142:143]
	v_pk_mul_f32 v[38:39], v[38:39], v[146:147]
	v_pk_mul_f32 v[36:37], v[36:37], v[144:145]
	v_pk_mul_f32 v[32:33], v[32:33], v[132:133]
	v_pk_mul_f32 v[28:29], v[28:29], v[136:137]
	v_pk_mul_f32 v[24:25], v[24:25], v[140:141]
	v_pk_mul_f32 v[34:35], v[34:35], v[134:135]
	v_pk_mul_f32 v[30:31], v[30:31], v[138:139]
	v_pk_mul_f32 v[26:27], v[26:27], v[142:143]
	v_pk_mul_f32 v[22:23], v[22:23], v[146:147]
	v_pk_mul_f32 v[20:21], v[20:21], v[144:145]
	v_pk_mul_f32 v[16:17], v[16:17], v[132:133]
	v_pk_mul_f32 v[12:13], v[12:13], v[136:137]
	v_pk_mul_f32 v[8:9], v[8:9], v[140:141]
	v_pk_mul_f32 v[18:19], v[18:19], v[134:135]
	v_pk_mul_f32 v[14:15], v[14:15], v[138:139]
	v_pk_mul_f32 v[10:11], v[10:11], v[142:143]
	v_pk_mul_f32 v[6:7], v[6:7], v[146:147]
	v_pk_mul_f32 v[4:5], v[4:5], v[144:145]
; __device__ __forceinline__ void partialSM(f32x16& p0, f32x16& p1, float& m_reg, float& mn, float& alpha) {
;   constexpr float C = SCALE * 1.4426950408889634f;
;   float pmax = p0[0]; for (int r = 1; r < 16; ++r) pmax = fmaxf(pmax, p0[r]); for (int r = 0; r < 16; ++r) pmax = fmaxf(pmax, p1[r]);
;   { auto rr = __builtin_amdgcn_permlane32_swap(__float_as_uint(pmax), __float_as_uint(pmax), false, false);
;     pmax = fmaxf(__uint_as_float(rr[0]), __uint_as_float(rr[1])); }
;   if (__builtin_expect(__all(pmax - m_reg <= THR / SCALE), 1)) { mn = m_reg; alpha = 1.f; }
;   else { mn = fmaxf(m_reg, pmax); alpha = __builtin_amdgcn_exp2f((m_reg - mn) * C); m_reg = mn; }
;   float mnC = -mn * C;
;   for (int r = 0; r < 16; ++r) p0[r] = fmaf(p0[r], C, mnC); for (int r = 0; r < 16; ++r) p1[r] = fmaf(p1[r], C, mnC);
;   for (int r = 0; r < 16; ++r) p0[r] = __builtin_amdgcn_exp2f(p0[r]);
; }
; __device__ __forceinline__ void finishSM(f32x16& p0, f32x16& p1, float alpha, float& l_reg, bf16x8& pa0, bf16x8& pa1, bf16x8& pa2, bf16x8& pa3) {
;   for (int r = 0; r < 16; ++r) p1[r] = __builtin_amdgcn_exp2f(p1[r]);
;   float ps = 0; for (int r = 0; r < 16; ++r) ps += p0[r]; for (int r = 0; r < 16; ++r) ps += p1[r];
;   { auto rr = __builtin_amdgcn_permlane32_swap(__float_as_uint(ps), __float_as_uint(ps), false, false);
;     ps = __uint_as_float(rr[0]) + __uint_as_float(rr[1]); }
;   l_reg = l_reg * alpha + ps;
;     ...
;   PK4(p0, 0, pa0); PK4(p0, 8, pa1); PK4(p1, 0, pa2); PK4(p1, 8, pa3);
;     ...
; }
; __device__ __forceinline__ void qkt(f32x16& p0, f32x16& p1, const u16* Ks, const bf16x8* qr, int r32, int hi) {
;   p0 = f32x16{}; p1 = f32x16{};
;   for (int d0 = 0; d0 < 8; ++d0) { int cb = (d0 * 16 + hi * 8) * 2;
;     bf16x8 b0 = *reinterpret_cast<const bf16x8*>((const char*)Ks + KSWZ(r32, cb));
;     bf16x8 b1 = *reinterpret_cast<const bf16x8*>((const char*)Ks + KSWZ(32 + r32, cb));
;     p0 = __builtin_amdgcn_mfma_f32_32x32x16_bf16(b0, qr[d0], p0, 0, 0, 0);
;     p1 = __builtin_amdgcn_mfma_f32_32x32x16_bf16(b1, qr[d0], p1, 0, 0, 0); }
; }
.LBB0_478:
	v_cndmask_b32_e64 v2, v2, v166, s[6:7]
	v_mul_f32_e32 v140, 0xbe0293ee, v2
	v_fmamk_f32 v93, v93, 0x3e0293ee, v140
	v_exp_f32_e32 v221, v93
	v_fmamk_f32 v84, v84, 0x3e0293ee, v140
	v_fmamk_f32 v85, v85, 0x3e0293ee, v140
	v_fmamk_f32 v86, v86, 0x3e0293ee, v140
	v_fmamk_f32 v87, v87, 0x3e0293ee, v140
	v_fmamk_f32 v88, v88, 0x3e0293ee, v140
	v_fmamk_f32 v89, v89, 0x3e0293ee, v140
	v_fmamk_f32 v90, v90, 0x3e0293ee, v140
	v_fmamk_f32 v91, v91, 0x3e0293ee, v140
	v_fmamk_f32 v92, v92, 0x3e0293ee, v140
	v_fmamk_f32 v94, v94, 0x3e0293ee, v140
	v_fmamk_f32 v95, v95, 0x3e0293ee, v140
	v_fmamk_f32 v96, v96, 0x3e0293ee, v140
	v_fmamk_f32 v97, v97, 0x3e0293ee, v140
	v_fmamk_f32 v98, v98, 0x3e0293ee, v140
	v_fmamk_f32 v99, v99, 0x3e0293ee, v140
	v_fmamk_f32 v141, v68, 0x3e0293ee, v140
	v_fmamk_f32 v142, v69, 0x3e0293ee, v140
	v_fmamk_f32 v143, v70, 0x3e0293ee, v140
	v_fmamk_f32 v144, v71, 0x3e0293ee, v140
	v_fmamk_f32 v145, v72, 0x3e0293ee, v140
	v_fmamk_f32 v146, v73, 0x3e0293ee, v140
	v_fmamk_f32 v147, v74, 0x3e0293ee, v140
	v_fmamk_f32 v166, v75, 0x3e0293ee, v140
	v_fmamk_f32 v203, v76, 0x3e0293ee, v140
	v_fmamk_f32 v204, v77, 0x3e0293ee, v140
	v_fmamk_f32 v205, v78, 0x3e0293ee, v140
	v_fmamk_f32 v206, v79, 0x3e0293ee, v140
	v_fmamk_f32 v207, v80, 0x3e0293ee, v140
	v_fmamk_f32 v208, v81, 0x3e0293ee, v140
	v_fmamk_f32 v209, v82, 0x3e0293ee, v140
	v_fmac_f32_e32 v140, 0x3e0293ee, v83
	v_exp_f32_e32 v210, v84
	v_exp_f32_e32 v211, v85
	v_exp_f32_e32 v212, v86
	v_exp_f32_e32 v213, v87
	v_exp_f32_e32 v214, v88
	v_exp_f32_e32 v215, v89
	v_exp_f32_e32 v216, v90
	v_exp_f32_e32 v217, v91
	v_exp_f32_e32 v218, v92
	v_exp_f32_e32 v222, v94
	v_exp_f32_e32 v223, v95
	v_exp_f32_e32 v224, v96
	v_exp_f32_e32 v225, v97
	v_exp_f32_e32 v226, v98
	v_exp_f32_e32 v227, v99
	s_waitcnt lgkmcnt(0)
	s_barrier
	s_setprio 1
	v_add_u32_e32 v254, s95, v189
	ds_read_b128 v[68:71], v254 offset:49152
	ds_read_b128 v[72:75], v254 offset:49280
	v_add_u32_e32 v254, s95, v190
	ds_read_b128 v[76:79], v254 offset:49152
	ds_read_b128 v[80:83], v254 offset:49280
	v_add_u32_e32 v254, s95, v191
	ds_read_b128 v[228:231], v254 offset:49152
	ds_read_b128 v[232:235], v254 offset:49280
	v_add_u32_e32 v254, s95, v192
	ds_read_b128 v[236:239], v254 offset:49152
	ds_read_b128 v[240:243], v254 offset:49280
	v_add_u32_e32 v254, s95, v189
	ds_read_b128 v[246:249], v254 offset:57344
	ds_read_b128 v[250:253], v254 offset:57472
	s_waitcnt lgkmcnt(9)
	v_mfma_f32_32x32x16_bf16 v[84:99], v[68:71], v[100:103], 0
	s_waitcnt lgkmcnt(8)
	v_mfma_f32_32x32x16_bf16 v[84:99], v[72:75], v[116:119], v[84:99]
	s_waitcnt lgkmcnt(7)
	v_mfma_f32_32x32x16_bf16 v[84:99], v[76:79], v[104:107], v[84:99]
	s_waitcnt lgkmcnt(6)
	v_mfma_f32_32x32x16_bf16 v[84:99], v[80:83], v[120:123], v[84:99]
	s_waitcnt lgkmcnt(5)
	v_mfma_f32_32x32x16_bf16 v[84:99], v[228:231], v[108:111], v[84:99]
	v_add_u32_e32 v254, s95, v190
	ds_read_b128 v[228:231], v254 offset:57344
	s_waitcnt lgkmcnt(5)
	v_mfma_f32_32x32x16_bf16 v[84:99], v[232:235], v[124:127], v[84:99]
	ds_read_b128 v[232:235], v254 offset:57472
	s_waitcnt lgkmcnt(5)
	v_mfma_f32_32x32x16_bf16 v[84:99], v[236:239], v[112:115], v[84:99]
	v_add_u32_e32 v254, s95, v191
	ds_read_b128 v[236:239], v254 offset:57344
	s_waitcnt lgkmcnt(5)
	v_mfma_f32_32x32x16_bf16 v[84:99], v[240:243], v[128:131], v[84:99]
	ds_read_b128 v[240:243], v254 offset:57472
	s_waitcnt lgkmcnt(5)
	v_mfma_f32_32x32x16_bf16 v[68:83], v[246:249], v[100:103], 0
	v_add_u32_e32 v254, s95, v192
	ds_read_b128 v[246:249], v254 offset:57344
	s_waitcnt lgkmcnt(5)
	v_mfma_f32_32x32x16_bf16 v[68:83], v[250:253], v[116:119], v[68:83]
	ds_read_b128 v[250:253], v254 offset:57472
	s_waitcnt lgkmcnt(5)
	v_mfma_f32_32x32x16_bf16 v[68:83], v[228:231], v[104:107], v[68:83]
	s_waitcnt lgkmcnt(4)
	v_mfma_f32_32x32x16_bf16 v[68:83], v[232:235], v[120:123], v[68:83]
	s_waitcnt lgkmcnt(3)
	v_mfma_f32_32x32x16_bf16 v[68:83], v[236:239], v[108:111], v[68:83]
	s_waitcnt lgkmcnt(2)
	v_mfma_f32_32x32x16_bf16 v[68:83], v[240:243], v[124:127], v[68:83]
	s_waitcnt lgkmcnt(1)
	v_mfma_f32_32x32x16_bf16 v[68:83], v[246:249], v[112:115], v[68:83]
	s_waitcnt lgkmcnt(0)
	v_mfma_f32_32x32x16_bf16 v[68:83], v[250:253], v[128:131], v[68:83]
	s_barrier
	s_setprio 0
	v_exp_f32_e32 v140, v140
	v_exp_f32_e32 v139, v166
	v_add_f32_e32 v166, 0, v210
	v_add_f32_e32 v166, v211, v166
	v_add_f32_e32 v166, v212, v166
	v_add_f32_e32 v166, v213, v166
	v_add_f32_e32 v166, v214, v166
	v_add_f32_e32 v166, v215, v166
	v_add_f32_e32 v166, v216, v166
	v_add_f32_e32 v166, v217, v166
	v_add_f32_e32 v166, v218, v166
	v_add_f32_e32 v166, v221, v166
	v_add_f32_e32 v166, v222, v166
	v_add_f32_e32 v166, v223, v166
	v_exp_f32_e32 v132, v141
	v_add_f32_e32 v166, v224, v166
	v_exp_f32_e32 v133, v142
	v_add_f32_e32 v166, v225, v166
	v_exp_f32_e32 v134, v143
	v_add_f32_e32 v166, v226, v166
	v_exp_f32_e32 v135, v144
	v_add_f32_e32 v166, v227, v166
	v_exp_f32_e32 v136, v145
	v_add_f32_e32 v166, v132, v166
	v_exp_f32_e32 v137, v146
	v_add_f32_e32 v166, v133, v166
	v_exp_f32_e32 v138, v147
	v_add_f32_e32 v166, v134, v166
	v_add_f32_e32 v166, v135, v166
	v_exp_f32_e32 v141, v203
	v_add_f32_e32 v166, v136, v166
	v_exp_f32_e32 v142, v204
	v_add_f32_e32 v166, v137, v166
	v_exp_f32_e32 v143, v205
	v_add_f32_e32 v166, v138, v166
	v_exp_f32_e32 v144, v206
	v_add_f32_e32 v166, v139, v166
	v_exp_f32_e32 v145, v207
	v_add_f32_e32 v166, v141, v166
	v_exp_f32_e32 v146, v208
	v_add_f32_e32 v166, v142, v166
	v_exp_f32_e32 v147, v209
	v_add_f32_e32 v166, v143, v166
	v_add_f32_e32 v166, v144, v166
	v_add_f32_e32 v166, v145, v166
	v_add_f32_e32 v166, v146, v166
	v_add_f32_e32 v166, v147, v166
; __device__ __forceinline__ void finishSM(f32x16& p0, f32x16& p1, float alpha, float& l_reg, bf16x8& pa0, bf16x8& pa1, bf16x8& pa2, bf16x8& pa3) {
;     ...
;   { auto rr = __builtin_amdgcn_permlane32_swap(__float_as_uint(ps), __float_as_uint(ps), false, false);
;     ps = __uint_as_float(rr[0]) + __uint_as_float(rr[1]); }
;   l_reg = l_reg * alpha + ps;
;     ...
;   PK4(p0, 0, pa0); PK4(p0, 8, pa1); PK4(p1, 0, pa2); PK4(p1, 8, pa3);
;     ...
; }
; __device__ __forceinline__ void qkt(f32x16& p0, f32x16& p1, const u16* Ks, const bf16x8* qr, int r32, int hi) {
;   p0 = f32x16{}; p1 = f32x16{};
;   for (int d0 = 0; d0 < 8; ++d0) { int cb = (d0 * 16 + hi * 8) * 2;
;     bf16x8 b0 = *reinterpret_cast<const bf16x8*>((const char*)Ks + KSWZ(r32, cb));
;     bf16x8 b1 = *reinterpret_cast<const bf16x8*>((const char*)Ks + KSWZ(32 + r32, cb));
;     p0 = __builtin_amdgcn_mfma_f32_32x32x16_bf16(b0, qr[d0], p0, 0, 0, 0);
;     p1 = __builtin_amdgcn_mfma_f32_32x32x16_bf16(b1, qr[d0], p1, 0, 0, 0); }
; }
; __device__ __forceinline__ void qkt_lds(f32x16& p0, f32x16& p1, const u16* Ks, const char* qs, int r32, int hi) {
;   p0 = f32x16{}; p1 = f32x16{};
;   for (int d0 = 0; d0 < 8; ++d0) { int cb = (d0 * 16 + hi * 8) * 2;
;     bf16x8 q = *reinterpret_cast<const bf16x8*>(qs + d0 * 1024);
;     bf16x8 b0 = *reinterpret_cast<const bf16x8*>((const char*)Ks + KSWZ(r32, cb));
;     bf16x8 b1 = *reinterpret_cast<const bf16x8*>((const char*)Ks + KSWZ(32 + r32, cb));
;     p0 = __builtin_amdgcn_mfma_f32_32x32x16_bf16(b0, q, p0, 0, 0, 0);
;     p1 = __builtin_amdgcn_mfma_f32_32x32x16_bf16(b1, q, p1, 0, 0, 0); }
; }
; __device__ __forceinline__ int v_st(int k, int c) { const int kk = (k & ~0xC) | ((k & 4) << 1) | ((k & 8) >> 1); return ((kk >> 3) * 4 + (c >> 5)) * 512 + ((kk & 7) * 32 + (c & 31)) * 2; }
; __device__ __forceinline__ int v_rd_base(int lane) { return ((lane & 3) << 3) | (((lane >> 2) & 3) << 6) | (((lane >> 4) & 1) << 5) | (((lane >> 5) & 1) << 8); }
; template <int OFF> __device__ __forceinline__ s16x4 tr_read(int vb) {
;   s16x4 r; asm volatile("ds_read_b64_tr_b16 %0, %1 offset:%2" : "=&v"(r) : "v"(vb), "i"(OFF) : "memory"); return r;
; }
; template <int D0> __device__ __forceinline__ void pv_one(f32x16& od, int vb, bf16x8 pa0, bf16x8 pa1, bf16x8 pa2, bf16x8 pa3) {
	v_add_f32_e32 v219, v140, v166
	v_mov_b32_e32 v220, v219
	s_nop 1
	v_permlane32_swap_b32_e32 v219, v220
	v_cvt_pk_bf16_f32 v204, v210, v211
	v_cvt_pk_bf16_f32 v205, v212, v213
	v_cvt_pk_bf16_f32 v206, v214, v215
	v_cvt_pk_bf16_f32 v207, v216, v217
	v_cvt_pk_bf16_f32 v208, v218, v221
	v_cvt_pk_bf16_f32 v209, v222, v223
	v_cvt_pk_bf16_f32 v210, v224, v225
	v_cvt_pk_bf16_f32 v211, v226, v227
	v_cvt_pk_bf16_f32 v212, v132, v133
	v_cvt_pk_bf16_f32 v213, v134, v135
	v_cvt_pk_bf16_f32 v214, v136, v137
	v_cvt_pk_bf16_f32 v215, v138, v139
	v_cvt_pk_bf16_f32 v222, v141, v142
	v_cvt_pk_bf16_f32 v223, v143, v144
	v_cvt_pk_bf16_f32 v224, v145, v146
	v_cvt_pk_bf16_f32 v225, v147, v140
	s_nop 0
	v_permlane32_swap_b32_e32 v204, v206
	v_permlane32_swap_b32_e32 v205, v207
	v_permlane32_swap_b32_e32 v208, v210
	v_permlane32_swap_b32_e32 v209, v211
	v_permlane32_swap_b32_e32 v212, v214
	v_permlane32_swap_b32_e32 v213, v215
	v_permlane32_swap_b32_e32 v222, v224
	v_permlane32_swap_b32_e32 v223, v225
	s_min_u32 s7, s16, s90
	s_add_i32 s7, s7, s88
	s_lshl_b32 s7, s7, 6
	v_add_u32_e32 v244, s7, v167
	v_add_u32_e32 v245, s7, v185
	v_lshl_or_b32 v244, v244, 8, v182
	v_lshl_or_b32 v245, v245, 8, v182
	global_load_dwordx4 v[136:139], v244, s[58:59]
	global_load_dwordx4 v[132:135], v245, s[58:59]
	global_load_dwordx4 v[144:147], v244, s[64:65]
	global_load_dwordx4 v[140:143], v245, s[64:65]
	v_add_u32_e32 v254, s93, v197
	ds_read_b64_tr_b16 v[230:231], v254 offset:0
	ds_read_b64_tr_b16 v[232:233], v254 offset:2048
	ds_read_b64_tr_b16 v[234:235], v254 offset:4096
	ds_read_b64_tr_b16 v[236:237], v254 offset:6144
	ds_read_b64_tr_b16 v[238:239], v254 offset:8192
	ds_read_b64_tr_b16 v[240:241], v254 offset:10240
	ds_read_b64_tr_b16 v[242:243], v254 offset:12288
	ds_read_b64_tr_b16 v[244:245], v254 offset:14336
	ds_read_b64_tr_b16 v[246:247], v254 offset:512
	ds_read_b64_tr_b16 v[248:249], v254 offset:2560
	s_barrier
	s_setprio 1
	s_waitcnt lgkmcnt(6)
	v_mfma_f32_32x32x16_bf16 v[52:67], v[204:207], v[230:233], v[52:67]
	ds_read_b64_tr_b16 v[250:251], v254 offset:4608
	ds_read_b64_tr_b16 v[252:253], v254 offset:6656
	v_mfma_f32_32x32x16_bf16 v[52:67], v[208:211], v[234:237], v[52:67]
	ds_read_b64_tr_b16 v[230:231], v254 offset:8704
	ds_read_b64_tr_b16 v[232:233], v254 offset:10752
	s_waitcnt lgkmcnt(6)
	v_mfma_f32_32x32x16_bf16 v[52:67], v[212:215], v[238:241], v[52:67]
	ds_read_b64_tr_b16 v[234:235], v254 offset:12800
	ds_read_b64_tr_b16 v[236:237], v254 offset:14848
	v_mfma_f32_32x32x16_bf16 v[52:67], v[222:225], v[242:245], v[52:67]
	ds_read_b64_tr_b16 v[238:239], v254 offset:1024
	ds_read_b64_tr_b16 v[240:241], v254 offset:3072
	s_waitcnt lgkmcnt(6)
	v_mfma_f32_32x32x16_bf16 v[36:51], v[204:207], v[246:249], v[36:51]
	ds_read_b64_tr_b16 v[242:243], v254 offset:5120
	ds_read_b64_tr_b16 v[244:245], v254 offset:7168
	v_mfma_f32_32x32x16_bf16 v[36:51], v[208:211], v[250:253], v[36:51]
	ds_read_b64_tr_b16 v[246:247], v254 offset:9216
	ds_read_b64_tr_b16 v[248:249], v254 offset:11264
	s_waitcnt lgkmcnt(6)
	v_mfma_f32_32x32x16_bf16 v[36:51], v[212:215], v[230:233], v[36:51]
	ds_read_b64_tr_b16 v[250:251], v254 offset:13312
	ds_read_b64_tr_b16 v[252:253], v254 offset:15360
	v_mfma_f32_32x32x16_bf16 v[36:51], v[222:225], v[234:237], v[36:51]
	ds_read_b64_tr_b16 v[230:231], v254 offset:1536
	ds_read_b64_tr_b16 v[232:233], v254 offset:3584
	s_waitcnt lgkmcnt(6)
	v_mfma_f32_32x32x16_bf16 v[20:35], v[204:207], v[238:241], v[20:35]
	ds_read_b64_tr_b16 v[234:235], v254 offset:5632
	ds_read_b64_tr_b16 v[236:237], v254 offset:7680
	v_mfma_f32_32x32x16_bf16 v[20:35], v[208:211], v[242:245], v[20:35]
	ds_read_b64_tr_b16 v[238:239], v254 offset:9728
	ds_read_b64_tr_b16 v[240:241], v254 offset:11776
	s_waitcnt lgkmcnt(6)
	v_mfma_f32_32x32x16_bf16 v[20:35], v[212:215], v[246:249], v[20:35]
	ds_read_b64_tr_b16 v[242:243], v254 offset:13824
	ds_read_b64_tr_b16 v[244:245], v254 offset:15872
	v_mfma_f32_32x32x16_bf16 v[20:35], v[222:225], v[250:253], v[20:35]
	s_waitcnt lgkmcnt(4)
	v_mfma_f32_32x32x16_bf16 v[4:19], v[204:207], v[230:233], v[4:19]
	v_mfma_f32_32x32x16_bf16 v[4:19], v[208:211], v[234:237], v[4:19]
	s_waitcnt lgkmcnt(0)
	v_mfma_f32_32x32x16_bf16 v[4:19], v[212:215], v[238:241], v[4:19]
	v_mfma_f32_32x32x16_bf16 v[4:19], v[222:225], v[242:245], v[4:19]
	s_barrier
; __device__ __forceinline__ void partialSM(f32x16& p0, f32x16& p1, float& m_reg, float& mn, float& alpha) {
;   constexpr float C = SCALE * 1.4426950408889634f;
;   float pmax = p0[0]; for (int r = 1; r < 16; ++r) pmax = fmaxf(pmax, p0[r]); for (int r = 0; r < 16; ++r) pmax = fmaxf(pmax, p1[r]);
;   { auto rr = __builtin_amdgcn_permlane32_swap(__float_as_uint(pmax), __float_as_uint(pmax), false, false);
;     pmax = fmaxf(__uint_as_float(rr[0]), __uint_as_float(rr[1])); }
;   if (__builtin_expect(__all(pmax - m_reg <= THR / SCALE), 1)) { mn = m_reg; alpha = 1.f; }
;   else { mn = fmaxf(m_reg, pmax); alpha = __builtin_amdgcn_exp2f((m_reg - mn) * C); m_reg = mn; }
	s_setprio 0
	s_add_i32 s30, s94, 0
	v_add_u32_e32 v203, s30, v184
	s_waitcnt vmcnt(4)
	ds_write_b128 v203, v[152:155]
	v_add_u32_e32 v152, s30, v186
	ds_write_b128 v152, v[148:151]
	v_add_u32_e32 v148, s30, v187
	ds_write_b128 v148, v[160:163] offset:49152
	v_add_u32_e32 v148, s30, v188
	s_waitcnt vmcnt(4)
	ds_write_b128 v148, v[156:159] offset:49152
	v_max_f32_e32 v166, v85, v85
	v_max_f32_e32 v203, v84, v84
	v_max_f32_e32 v166, v203, v166
	v_max3_f32 v166, v166, v86, v87
	v_max3_f32 v166, v166, v88, v89
	v_max3_f32 v166, v166, v90, v91
	v_max3_f32 v166, v166, v92, v93
	v_max3_f32 v166, v166, v94, v95
	v_max3_f32 v166, v166, v96, v97
	v_max3_f32 v166, v166, v98, v99
	v_max3_f32 v166, v166, v68, v69
	v_max3_f32 v166, v166, v70, v71
	v_max3_f32 v166, v166, v72, v73
	v_max3_f32 v166, v166, v74, v75
	v_max3_f32 v166, v166, v76, v77
	v_max3_f32 v166, v166, v78, v79
	v_max3_f32 v166, v166, v80, v81
	v_max3_f32 v166, v166, v82, v83
	v_mov_b32_e32 v203, v166
	s_nop 1
	v_permlane32_swap_b32_e32 v166, v203
	v_max_f32_e32 v203, v203, v203
	v_max_f32_e32 v166, v166, v166
	v_max_f32_e32 v166, v166, v203
	v_sub_f32_e32 v203, v166, v2
	v_cmp_ge_f32_e32 vcc, s74, v203
	v_max_f32_e32 v203, v2, v2
	v_max_f32_e32 v166, v203, v166
	v_sub_f32_e32 v203, v2, v166
	v_mul_f32_e32 v203, 0x3e0293ee, v203
	v_exp_f32_e32 v203, v203
	s_cmp_eq_u64 vcc, exec
	s_cselect_b64 s[6:7], -1, 0
	v_cndmask_b32_e64 v221, v203, 1.0, s[6:7]
	v_cmp_gt_f32_e32 vcc, 1.0, v221
	s_cbranch_vccz .LBB0_482
	s_and_saveexec_b64 s[66:67], s[4:5]
	ds_write_b32 v183, v221 offset:128
	s_or_b64 exec, exec, s[66:67]
	s_waitcnt lgkmcnt(0)
	v_add_u32_e32 v160, v181, v180
	ds_read_b128 v[148:151], v160 offset:224
	ds_read_b128 v[152:155], v160 offset:192
	ds_read_b128 v[156:159], v160 offset:160
	ds_read_b128 v[160:163], v160 offset:128
	s_waitcnt lgkmcnt(3)
	v_pk_mul_f32 v[64:65], v[64:65], v[148:149]
	s_waitcnt lgkmcnt(2)
	v_pk_mul_f32 v[60:61], v[60:61], v[152:153]
	s_waitcnt lgkmcnt(1)
	v_pk_mul_f32 v[56:57], v[56:57], v[156:157]
	v_pk_mul_f32 v[66:67], v[66:67], v[150:151]
	v_pk_mul_f32 v[62:63], v[62:63], v[154:155]
	v_pk_mul_f32 v[58:59], v[58:59], v[158:159]
	s_waitcnt lgkmcnt(0)
	v_pk_mul_f32 v[54:55], v[54:55], v[162:163]
	v_pk_mul_f32 v[52:53], v[52:53], v[160:161]
	v_pk_mul_f32 v[48:49], v[48:49], v[148:149]
	v_pk_mul_f32 v[44:45], v[44:45], v[152:153]
	v_pk_mul_f32 v[40:41], v[40:41], v[156:157]
	v_pk_mul_f32 v[50:51], v[50:51], v[150:151]
	v_pk_mul_f32 v[46:47], v[46:47], v[154:155]
	v_pk_mul_f32 v[42:43], v[42:43], v[158:159]
	v_pk_mul_f32 v[38:39], v[38:39], v[162:163]
	v_pk_mul_f32 v[36:37], v[36:37], v[160:161]
	v_pk_mul_f32 v[32:33], v[32:33], v[148:149]
	v_pk_mul_f32 v[28:29], v[28:29], v[152:153]
	v_pk_mul_f32 v[24:25], v[24:25], v[156:157]
	v_pk_mul_f32 v[34:35], v[34:35], v[150:151]
	v_pk_mul_f32 v[30:31], v[30:31], v[154:155]
	v_pk_mul_f32 v[26:27], v[26:27], v[158:159]
	v_pk_mul_f32 v[22:23], v[22:23], v[162:163]
	v_pk_mul_f32 v[20:21], v[20:21], v[160:161]
	v_pk_mul_f32 v[16:17], v[16:17], v[148:149]
	v_pk_mul_f32 v[12:13], v[12:13], v[152:153]
	v_pk_mul_f32 v[8:9], v[8:9], v[156:157]
	v_pk_mul_f32 v[18:19], v[18:19], v[150:151]
	v_pk_mul_f32 v[14:15], v[14:15], v[154:155]
	v_pk_mul_f32 v[10:11], v[10:11], v[158:159]
	v_pk_mul_f32 v[6:7], v[6:7], v[162:163]
	v_pk_mul_f32 v[4:5], v[4:5], v[160:161]

; #define SBAR() __builtin_amdgcn_sched_barrier(0)
; #define QKT(P0, P1, KS) do { if (MODE == 1) qkt_lds(P0, P1, KS, qs, r32, hi); else qkt(P0, P1, KS, qr, r32, hi); } while (0)
; __device__ __forceinline__ void finishSM(f32x16& p0, f32x16& p1, float alpha, float& l_reg, bf16x8& pa0, bf16x8& pa1, bf16x8& pa2, bf16x8& pa3) {
;   for (int r = 0; r < 16; ++r) p1[r] = __builtin_amdgcn_exp2f(p1[r]);
;   float ps = 0; for (int r = 0; r < 16; ++r) ps += p0[r]; for (int r = 0; r < 16; ++r) ps += p1[r];
;   { auto rr = __builtin_amdgcn_permlane32_swap(__float_as_uint(ps), __float_as_uint(ps), false, false);
;     ps = __uint_as_float(rr[0]) + __uint_as_float(rr[1]); }
;   l_reg = l_reg * alpha + ps;
;     ...
;   PK4(p0, 0, pa0); PK4(p0, 8, pa1); PK4(p1, 0, pa2); PK4(p1, 8, pa3);
;     ...
; }
; __device__ __forceinline__ void qkt(f32x16& p0, f32x16& p1, const u16* Ks, const bf16x8* qr, int r32, int hi) {
;   p0 = f32x16{}; p1 = f32x16{};
;   for (int d0 = 0; d0 < 8; ++d0) { int cb = (d0 * 16 + hi * 8) * 2;
;     bf16x8 b0 = *reinterpret_cast<const bf16x8*>((const char*)Ks + KSWZ(r32, cb));
;     bf16x8 b1 = *reinterpret_cast<const bf16x8*>((const char*)Ks + KSWZ(32 + r32, cb));
;     p0 = __builtin_amdgcn_mfma_f32_32x32x16_bf16(b0, qr[d0], p0, 0, 0, 0);
;     p1 = __builtin_amdgcn_mfma_f32_32x32x16_bf16(b1, qr[d0], p1, 0, 0, 0); }
; }
; template <int MODE> ...
;     ...
;     for (int j = 1; j + 1 < NT; j += 2) {
;       const int s0_ = sj, s1_ = sj == 2 ? 0 : sj + 1, s2_ = s1_ == 2 ? 0 : s1_ + 1;
;       SBAR(); QKT(pB0, pB1, (u16*)((char*)K_lds + s0_ * SHM_K));
;       finishSM(pA0, pA1, alA, l_reg, pa0, pa1, pa2, pa3); SBAR();
;       { const int tn = (j + 2 < NT) ? j + 2 : NT - 1; SLOAD(SO, tn); } SBAR();
.Lstg_loop:
	s_barrier
	s_add_i32 s7, s89, 1
	s_cmp_lg_u32 s89, 2
	s_cselect_b32 s66, s7, 0
	s_add_i32 s7, s66, 1
	s_cmp_lg_u32 s66, 2
	s_mov_b32 s6, s89
	s_cselect_b32 s89, s7, 0
	s_lshl_b32 s93, s6, 14
	s_add_i32 s6, s93, 0
	s_setprio 1
	v_add_u32_e32 v254, s6, v189
	ds_read_b128 v[68:71], v254 offset:49152
	ds_read_b128 v[72:75], v254 offset:49280
	v_add_u32_e32 v254, s6, v190
	ds_read_b128 v[76:79], v254 offset:49152
	ds_read_b128 v[80:83], v254 offset:49280
	v_add_u32_e32 v254, s6, v191
	ds_read_b128 v[220:223], v254 offset:49152
	ds_read_b128 v[224:227], v254 offset:49280
	v_add_u32_e32 v254, s6, v192
	ds_read_b128 v[228:231], v254 offset:49152
	ds_read_b128 v[232:235], v254 offset:49280
	v_add_u32_e32 v254, s6, v189
	ds_read_b128 v[236:239], v254 offset:57344
	ds_read_b128 v[240:243], v254 offset:57472
	s_waitcnt lgkmcnt(9)
	v_mfma_f32_32x32x16_bf16 v[84:99], v[68:71], v[100:103], 0
	s_waitcnt lgkmcnt(8)
	v_mfma_f32_32x32x16_bf16 v[84:99], v[72:75], v[116:119], v[84:99]
	s_waitcnt lgkmcnt(7)
	v_mfma_f32_32x32x16_bf16 v[84:99], v[76:79], v[104:107], v[84:99]
	s_waitcnt lgkmcnt(6)
	v_mfma_f32_32x32x16_bf16 v[84:99], v[80:83], v[120:123], v[84:99]
	s_waitcnt lgkmcnt(5)
	v_mfma_f32_32x32x16_bf16 v[84:99], v[220:223], v[108:111], v[84:99]
	v_add_u32_e32 v254, s6, v190
	ds_read_b128 v[220:223], v254 offset:57344
	s_waitcnt lgkmcnt(5)
	v_mfma_f32_32x32x16_bf16 v[84:99], v[224:227], v[124:127], v[84:99]
	ds_read_b128 v[224:227], v254 offset:57472
	s_waitcnt lgkmcnt(5)
	v_mfma_f32_32x32x16_bf16 v[84:99], v[228:231], v[112:115], v[84:99]
	v_add_u32_e32 v254, s6, v191
	ds_read_b128 v[228:231], v254 offset:57344
	s_waitcnt lgkmcnt(5)
	v_mfma_f32_32x32x16_bf16 v[84:99], v[232:235], v[128:131], v[84:99]
	ds_read_b128 v[232:235], v254 offset:57472
	s_waitcnt lgkmcnt(5)
	v_mfma_f32_32x32x16_bf16 v[68:83], v[236:239], v[100:103], 0
	v_add_u32_e32 v254, s6, v192
	ds_read_b128 v[236:239], v254 offset:57344
	s_waitcnt lgkmcnt(5)
	v_mfma_f32_32x32x16_bf16 v[68:83], v[240:243], v[116:119], v[68:83]
	ds_read_b128 v[240:243], v254 offset:57472
	s_waitcnt lgkmcnt(5)
	v_mfma_f32_32x32x16_bf16 v[68:83], v[220:223], v[104:107], v[68:83]
	s_waitcnt lgkmcnt(4)
	v_mfma_f32_32x32x16_bf16 v[68:83], v[224:227], v[120:123], v[68:83]
	s_waitcnt lgkmcnt(3)
	v_mfma_f32_32x32x16_bf16 v[68:83], v[228:231], v[108:111], v[68:83]
	s_waitcnt lgkmcnt(2)
	v_mfma_f32_32x32x16_bf16 v[68:83], v[232:235], v[124:127], v[68:83]
	s_waitcnt lgkmcnt(1)
	v_mfma_f32_32x32x16_bf16 v[68:83], v[236:239], v[112:115], v[68:83]
	s_waitcnt lgkmcnt(0)
	v_mfma_f32_32x32x16_bf16 v[68:83], v[240:243], v[128:131], v[68:83]
	s_barrier
	s_setprio 0
	v_exp_f32_e32 v160, v160
	v_exp_f32_e32 v161, v161
	v_exp_f32_e32 v158, v158
	v_exp_f32_e32 v159, v159
	v_exp_f32_e32 v156, v156
	v_exp_f32_e32 v157, v157
	v_exp_f32_e32 v154, v154
	v_exp_f32_e32 v155, v155
	v_exp_f32_e32 v152, v152
	v_exp_f32_e32 v153, v153
	v_exp_f32_e32 v150, v150
	v_exp_f32_e32 v151, v151
	v_exp_f32_e32 v148, v148
	v_exp_f32_e32 v149, v149
	v_exp_f32_e32 v2, v162
	v_exp_f32_e32 v162, v163
	v_add_f32_e32 v163, 0, v216
	v_add_f32_e32 v163, v218, v163
	v_add_f32_e32 v163, v214, v163
	v_add_f32_e32 v163, v217, v163
	v_add_f32_e32 v163, v213, v163
	v_add_f32_e32 v163, v215, v163
	v_add_f32_e32 v163, v211, v163
	v_add_f32_e32 v163, v212, v163
	v_add_f32_e32 v163, v208, v163
	v_add_f32_e32 v163, v210, v163
	v_add_f32_e32 v163, v207, v163
	v_add_f32_e32 v163, v209, v163
	v_add_f32_e32 v163, v204, v163
	v_add_f32_e32 v163, v206, v163
	v_add_f32_e32 v163, v203, v163
	v_add_f32_e32 v163, v205, v163
	v_add_f32_e32 v163, v2, v163
	v_add_f32_e32 v163, v162, v163
	v_add_f32_e32 v163, v160, v163
	v_add_f32_e32 v163, v161, v163
	v_add_f32_e32 v163, v158, v163
	v_add_f32_e32 v163, v159, v163
	v_add_f32_e32 v163, v156, v163
	v_add_f32_e32 v163, v157, v163
	v_add_f32_e32 v163, v154, v163
	v_add_f32_e32 v163, v155, v163
	v_add_f32_e32 v163, v152, v163
	v_add_f32_e32 v163, v153, v163
	v_add_f32_e32 v163, v150, v163
	v_add_f32_e32 v163, v151, v163
	v_add_f32_e32 v163, v148, v163
	v_add_f32_e32 v200, v149, v163
	v_mov_b32_e32 v201, v200
	v_cvt_pk_bf16_f32 v216, v216, v218
	v_cvt_pk_bf16_f32 v217, v214, v217
	v_cvt_pk_bf16_f32 v218, v213, v215
	v_cvt_pk_bf16_f32 v219, v211, v212
	v_cvt_pk_bf16_f32 v208, v208, v210
	v_cvt_pk_bf16_f32 v209, v207, v209
	v_cvt_pk_bf16_f32 v210, v204, v206
	v_cvt_pk_bf16_f32 v211, v203, v205
	v_cvt_pk_bf16_f32 v202, v2, v162
	v_cvt_pk_bf16_f32 v203, v160, v161
	v_cvt_pk_bf16_f32 v204, v158, v159
	v_permlane32_swap_b32_e32 v200, v201
	v_cvt_pk_bf16_f32 v205, v156, v157
	v_permlane32_swap_b32_e32 v202, v204
	v_cvt_pk_bf16_f32 v212, v154, v155
	v_cvt_pk_bf16_f32 v213, v152, v153
	v_cvt_pk_bf16_f32 v214, v150, v151
	v_cvt_pk_bf16_f32 v215, v148, v149
	v_permlane32_swap_b32_e32 v216, v218
	v_permlane32_swap_b32_e32 v217, v219
	v_permlane32_swap_b32_e32 v208, v210
	v_permlane32_swap_b32_e32 v209, v211
	v_permlane32_swap_b32_e32 v203, v205
	v_permlane32_swap_b32_e32 v212, v214
	v_permlane32_swap_b32_e32 v213, v215
	s_add_i32 s91, s16, -1
	s_min_u32 s7, s91, s90
	s_add_i32 s7, s7, s88
	s_lshl_b32 s7, s7, 6
	v_add_u32_e32 v244, s7, v167
	v_add_u32_e32 v245, s7, v185
	v_lshl_or_b32 v244, v244, 8, v182
	v_lshl_or_b32 v245, v245, 8, v182
	global_load_dwordx4 v[152:155], v244, s[58:59]
	global_load_dwordx4 v[148:151], v245, s[58:59]
	global_load_dwordx4 v[160:163], v244, s[64:65]
	global_load_dwordx4 v[156:159], v245, s[64:65]
	s_lshl_b32 s94, s89, 14
	v_add_u32_e32 v254, s94, v197
	ds_read_b64_tr_b16 v[220:221], v254 offset:0
	ds_read_b64_tr_b16 v[222:223], v254 offset:2048
	ds_read_b64_tr_b16 v[224:225], v254 offset:4096
	ds_read_b64_tr_b16 v[226:227], v254 offset:6144
	ds_read_b64_tr_b16 v[228:229], v254 offset:8192
	ds_read_b64_tr_b16 v[230:231], v254 offset:10240
	ds_read_b64_tr_b16 v[232:233], v254 offset:12288
	ds_read_b64_tr_b16 v[234:235], v254 offset:14336
	ds_read_b64_tr_b16 v[236:237], v254 offset:512
	ds_read_b64_tr_b16 v[238:239], v254 offset:2560
	s_barrier
; #define SBAR() __builtin_amdgcn_sched_barrier(0)
; __device__ __forceinline__ void partialSM(f32x16& p0, f32x16& p1, float& m_reg, float& mn, float& alpha) {
;   constexpr float C = SCALE * 1.4426950408889634f;
;   float pmax = p0[0]; for (int r = 1; r < 16; ++r) pmax = fmaxf(pmax, p0[r]); for (int r = 0; r < 16; ++r) pmax = fmaxf(pmax, p1[r]);
;   { auto rr = __builtin_amdgcn_permlane32_swap(__float_as_uint(pmax), __float_as_uint(pmax), false, false);
;     pmax = fmaxf(__uint_as_float(rr[0]), __uint_as_float(rr[1])); }
;   if (__builtin_expect(__all(pmax - m_reg <= THR / SCALE), 1)) { mn = m_reg; alpha = 1.f; }
;   else { mn = fmaxf(m_reg, pmax); alpha = __builtin_amdgcn_exp2f((m_reg - mn) * C); m_reg = mn; }
; template <int OFF> __device__ __forceinline__ s16x4 tr_read(int vb) {
;   s16x4 r; asm volatile("ds_read_b64_tr_b16 %0, %1 offset:%2" : "=&v"(r) : "v"(vb), "i"(OFF) : "memory"); return r;
; }
; template <int D0> __device__ __forceinline__ void pv_one(f32x16& od, int vb, bf16x8 pa0, bf16x8 pa1, bf16x8 pa2, bf16x8 pa3) {
;   const s16x4 l0 = tr_read<v_rd_off(D0, 0, 0)>(vb), h0 = tr_read<v_rd_off(D0, 0, 1)>(vb), l1 = tr_read<v_rd_off(D0, 1, 0)>(vb), h1 = tr_read<v_rd_off(D0, 1, 1)>(vb);
;   const s16x4 l2 = tr_read<v_rd_off(D0, 2, 0)>(vb), h2 = tr_read<v_rd_off(D0, 2, 1)>(vb), l3 = tr_read<v_rd_off(D0, 3, 0)>(vb), h3 = tr_read<v_rd_off(D0, 3, 1)>(vb);
;   asm volatile("s_waitcnt lgkmcnt(0)" ::: "memory"); SBAR();
;     ...
;   od = __builtin_amdgcn_mfma_f32_32x32x16_bf16(pa0, PK(l0, h0), od, 0, 0, 0);
;   od = __builtin_amdgcn_mfma_f32_32x32x16_bf16(pa1, PK(l1, h1), od, 0, 0, 0);
;   od = __builtin_amdgcn_mfma_f32_32x32x16_bf16(pa2, PK(l2, h2), od, 0, 0, 0);
;   od = __builtin_amdgcn_mfma_f32_32x32x16_bf16(pa3, PK(l3, h3), od, 0, 0, 0);
;     ...
; }
; __device__ __forceinline__ void pv_d0(f32x16* o, int vb, bf16x8 pa0, bf16x8 pa1, bf16x8 pa2, bf16x8 pa3) {
;   pv_one<0>(o[0], vb, pa0, pa1, pa2, pa3); pv_one<1>(o[1], vb, pa0, pa1, pa2, pa3); pv_one<2>(o[2], vb, pa0, pa1, pa2, pa3); pv_one<3>(o[3], vb, pa0, pa1, pa2, pa3);
	s_setprio 1
	s_waitcnt lgkmcnt(6)
	v_mfma_f32_32x32x16_bf16 v[52:67], v[216:219], v[220:223], v[52:67]
	ds_read_b64_tr_b16 v[240:241], v254 offset:4608
	ds_read_b64_tr_b16 v[242:243], v254 offset:6656
	v_mfma_f32_32x32x16_bf16 v[52:67], v[208:211], v[224:227], v[52:67]
	ds_read_b64_tr_b16 v[220:221], v254 offset:8704
	ds_read_b64_tr_b16 v[222:223], v254 offset:10752
	s_waitcnt lgkmcnt(6)
	v_mfma_f32_32x32x16_bf16 v[52:67], v[202:205], v[228:231], v[52:67]
	ds_read_b64_tr_b16 v[224:225], v254 offset:12800
	ds_read_b64_tr_b16 v[226:227], v254 offset:14848
	v_mfma_f32_32x32x16_bf16 v[52:67], v[212:215], v[232:235], v[52:67]
	ds_read_b64_tr_b16 v[228:229], v254 offset:1024
	ds_read_b64_tr_b16 v[230:231], v254 offset:3072
	s_waitcnt lgkmcnt(6)
	v_mfma_f32_32x32x16_bf16 v[36:51], v[216:219], v[236:239], v[36:51]
	ds_read_b64_tr_b16 v[232:233], v254 offset:5120
	ds_read_b64_tr_b16 v[234:235], v254 offset:7168
	v_mfma_f32_32x32x16_bf16 v[36:51], v[208:211], v[240:243], v[36:51]
	ds_read_b64_tr_b16 v[236:237], v254 offset:9216
	ds_read_b64_tr_b16 v[238:239], v254 offset:11264
	s_waitcnt lgkmcnt(6)
	v_mfma_f32_32x32x16_bf16 v[36:51], v[202:205], v[220:223], v[36:51]
	ds_read_b64_tr_b16 v[240:241], v254 offset:13312
	ds_read_b64_tr_b16 v[242:243], v254 offset:15360
	v_mfma_f32_32x32x16_bf16 v[36:51], v[212:215], v[224:227], v[36:51]
	ds_read_b64_tr_b16 v[220:221], v254 offset:1536
	ds_read_b64_tr_b16 v[222:223], v254 offset:3584
	s_waitcnt lgkmcnt(6)
	v_mfma_f32_32x32x16_bf16 v[20:35], v[216:219], v[228:231], v[20:35]
	ds_read_b64_tr_b16 v[224:225], v254 offset:5632
	ds_read_b64_tr_b16 v[226:227], v254 offset:7680
	v_mfma_f32_32x32x16_bf16 v[20:35], v[208:211], v[232:235], v[20:35]
	ds_read_b64_tr_b16 v[228:229], v254 offset:9728
	ds_read_b64_tr_b16 v[230:231], v254 offset:11776
	s_waitcnt lgkmcnt(6)
	v_mfma_f32_32x32x16_bf16 v[20:35], v[202:205], v[236:239], v[20:35]
	ds_read_b64_tr_b16 v[232:233], v254 offset:13824
	ds_read_b64_tr_b16 v[234:235], v254 offset:15872
	v_mfma_f32_32x32x16_bf16 v[20:35], v[212:215], v[240:243], v[20:35]
	s_waitcnt lgkmcnt(4)
	v_mfma_f32_32x32x16_bf16 v[4:19], v[216:219], v[220:223], v[4:19]
	s_waitcnt vmcnt(4)
	v_mfma_f32_32x32x16_bf16 v[4:19], v[208:211], v[224:227], v[4:19]
	s_waitcnt lgkmcnt(0)
	v_mfma_f32_32x32x16_bf16 v[4:19], v[202:205], v[228:231], v[4:19]
	v_mfma_f32_32x32x16_bf16 v[4:19], v[212:215], v[232:235], v[4:19]
	s_setprio 0
	s_lshl_b32 s92, s66, 14
	s_add_i32 s95, s92, 0
	v_add_u32_e32 v203, s95, v184
	ds_write_b128 v203, v[136:139]
	v_add_u32_e32 v136, s95, v186
	ds_write_b128 v136, v[132:135]
	v_add_u32_e32 v132, s95, v187
	ds_write_b128 v132, v[144:147] offset:49152
	v_add_u32_e32 v132, s95, v188
	s_waitcnt vmcnt(4)
	ds_write_b128 v132, v[140:143] offset:49152
	s_waitcnt lgkmcnt(0)
	s_barrier
	v_max_f32_e32 v2, v85, v85
	v_max_f32_e32 v202, v84, v84
	v_max_f32_e32 v2, v202, v2
	v_max3_f32 v2, v2, v86, v87
	v_max3_f32 v2, v2, v88, v89
	v_max3_f32 v2, v2, v90, v91
	v_max3_f32 v2, v2, v92, v93
	v_max3_f32 v2, v2, v94, v95
	v_max3_f32 v2, v2, v96, v97
	v_max3_f32 v2, v2, v98, v99
	v_max3_f32 v2, v2, v68, v69
	v_max3_f32 v2, v2, v70, v71
	v_max3_f32 v2, v2, v72, v73
	v_max3_f32 v2, v2, v74, v75
	v_max3_f32 v2, v2, v76, v77
	v_max3_f32 v2, v2, v78, v79
	v_max3_f32 v2, v2, v80, v81
	v_max3_f32 v2, v2, v82, v83
	v_mov_b32_e32 v202, v2
	s_nop 1
	v_permlane32_swap_b32_e32 v2, v202
	v_max_f32_e32 v202, v202, v202
	v_max_f32_e32 v2, v2, v2
	v_max_f32_e32 v2, v2, v202
	v_sub_f32_e32 v202, v2, v166
	v_cmp_ge_f32_e32 vcc, s74, v202
	v_max_f32_e32 v202, v166, v166
	v_max_f32_e32 v2, v202, v2
	v_sub_f32_e32 v202, v166, v2
	s_cmp_eq_u64 vcc, exec
	v_mul_f32_e32 v202, 0x3e0293ee, v202
	s_cselect_b64 s[6:7], -1, 0
	v_exp_f32_e32 v202, v202
	s_nop 0
	v_cndmask_b32_e64 v202, v202, 1.0, s[6:7]
	v_cmp_gt_f32_e32 vcc, 1.0, v202
	s_cbranch_vccz .Lstg_r1
	s_and_saveexec_b64 s[66:67], s[4:5]
	ds_write_b32 v183, v202 offset:128
	s_or_b64 exec, exec, s[66:67]
	s_waitcnt lgkmcnt(0)
	v_add_u32_e32 v144, v181, v180
	ds_read_b128 v[132:135], v144 offset:224
	ds_read_b128 v[136:139], v144 offset:192
	ds_read_b128 v[140:143], v144 offset:160
	ds_read_b128 v[144:147], v144 offset:128
	s_waitcnt lgkmcnt(3)
	v_pk_mul_f32 v[64:65], v[64:65], v[132:133]
	s_waitcnt lgkmcnt(2)
	v_pk_mul_f32 v[60:61], v[60:61], v[136:137]
	s_waitcnt lgkmcnt(1)
	v_pk_mul_f32 v[56:57], v[56:57], v[140:141]
	v_pk_mul_f32 v[66:67], v[66:67], v[134:135]
	v_pk_mul_f32 v[62:63], v[62:63], v[138:139]
	v_pk_mul_f32 v[58:59], v[58:59], v[142:143]
	s_waitcnt lgkmcnt(0)
	v_pk_mul_f32 v[54:55], v[54:55], v[146:147]
	v_pk_mul_f32 v[52:53], v[52:53], v[144:145]
	v_pk_mul_f32 v[48:49], v[48:49], v[132:133]
	v_pk_mul_f32 v[44:45], v[44:45], v[136:137]
	v_pk_mul_f32 v[40:41], v[40:41], v[140:141]
	v_pk_mul_f32 v[50:51], v[50:51], v[134:135]
	v_pk_mul_f32 v[46:47], v[46:47], v[138:139]
	v_pk_mul_f32 v[42:43], v[42:43], v[142:143]
	v_pk_mul_f32 v[38:39], v[38:39], v[146:147]
	v_pk_mul_f32 v[36:37], v[36:37], v[144:145]
	v_pk_mul_f32 v[32:33], v[32:33], v[132:133]
	v_pk_mul_f32 v[28:29], v[28:29], v[136:137]
	v_pk_mul_f32 v[24:25], v[24:25], v[140:141]
	v_pk_mul_f32 v[34:35], v[34:35], v[134:135]
	v_pk_mul_f32 v[30:31], v[30:31], v[138:139]
	v_pk_mul_f32 v[26:27], v[26:27], v[142:143]
	v_pk_mul_f32 v[22:23], v[22:23], v[146:147]
	v_pk_mul_f32 v[20:21], v[20:21], v[144:145]
	v_pk_mul_f32 v[16:17], v[16:17], v[132:133]
	v_pk_mul_f32 v[12:13], v[12:13], v[136:137]
	v_pk_mul_f32 v[8:9], v[8:9], v[140:141]
	v_pk_mul_f32 v[18:19], v[18:19], v[134:135]
	v_pk_mul_f32 v[14:15], v[14:15], v[138:139]
	v_pk_mul_f32 v[10:11], v[10:11], v[142:143]
	v_pk_mul_f32 v[6:7], v[6:7], v[146:147]
	v_pk_mul_f32 v[4:5], v[4:5], v[144:145]
; __device__ __forceinline__ void partialSM(f32x16& p0, f32x16& p1, float& m_reg, float& mn, float& alpha) {
;   constexpr float C = SCALE * 1.4426950408889634f;
;   float pmax = p0[0]; for (int r = 1; r < 16; ++r) pmax = fmaxf(pmax, p0[r]); for (int r = 0; r < 16; ++r) pmax = fmaxf(pmax, p1[r]);
;   { auto rr = __builtin_amdgcn_permlane32_swap(__float_as_uint(pmax), __float_as_uint(pmax), false, false);
;     pmax = fmaxf(__uint_as_float(rr[0]), __uint_as_float(rr[1])); }
;   if (__builtin_expect(__all(pmax - m_reg <= THR / SCALE), 1)) { mn = m_reg; alpha = 1.f; }
;   else { mn = fmaxf(m_reg, pmax); alpha = __builtin_amdgcn_exp2f((m_reg - mn) * C); m_reg = mn; }
;   float mnC = -mn * C;
;   for (int r = 0; r < 16; ++r) p0[r] = fmaf(p0[r], C, mnC); for (int r = 0; r < 16; ++r) p1[r] = fmaf(p1[r], C, mnC);
;   for (int r = 0; r < 16; ++r) p0[r] = __builtin_amdgcn_exp2f(p0[r]);
; }
; __device__ __forceinline__ void finishSM(f32x16& p0, f32x16& p1, float alpha, float& l_reg, bf16x8& pa0, bf16x8& pa1, bf16x8& pa2, bf16x8& pa3) {
;   for (int r = 0; r < 16; ++r) p1[r] = __builtin_amdgcn_exp2f(p1[r]);
;   float ps = 0; for (int r = 0; r < 16; ++r) ps += p0[r]; for (int r = 0; r < 16; ++r) ps += p1[r];
;   { auto rr = __builtin_amdgcn_permlane32_swap(__float_as_uint(ps), __float_as_uint(ps), false, false);
;     ps = __uint_as_float(rr[0]) + __uint_as_float(rr[1]); }
;   l_reg = l_reg * alpha + ps;
;     ...
;   PK4(p0, 0, pa0); PK4(p0, 8, pa1); PK4(p1, 0, pa2); PK4(p1, 8, pa3);
;     ...
; }
; __device__ __forceinline__ void qkt(f32x16& p0, f32x16& p1, const u16* Ks, const bf16x8* qr, int r32, int hi) {
;   p0 = f32x16{}; p1 = f32x16{};
;   for (int d0 = 0; d0 < 8; ++d0) { int cb = (d0 * 16 + hi * 8) * 2;
;     bf16x8 b0 = *reinterpret_cast<const bf16x8*>((const char*)Ks + KSWZ(r32, cb));
;     bf16x8 b1 = *reinterpret_cast<const bf16x8*>((const char*)Ks + KSWZ(32 + r32, cb));
;     p0 = __builtin_amdgcn_mfma_f32_32x32x16_bf16(b0, qr[d0], p0, 0, 0, 0);
;     p1 = __builtin_amdgcn_mfma_f32_32x32x16_bf16(b1, qr[d0], p1, 0, 0, 0); }
; }
.Lstg_r1:
	v_cndmask_b32_e64 v2, v2, v166, s[6:7]
	v_mul_f32_e32 v140, 0xbe0293ee, v2
	v_fmamk_f32 v93, v93, 0x3e0293ee, v140
	v_exp_f32_e32 v221, v93
	v_fmamk_f32 v84, v84, 0x3e0293ee, v140
	v_fmamk_f32 v85, v85, 0x3e0293ee, v140
	v_fmamk_f32 v86, v86, 0x3e0293ee, v140
	v_fmamk_f32 v87, v87, 0x3e0293ee, v140
	v_fmamk_f32 v88, v88, 0x3e0293ee, v140
	v_fmamk_f32 v89, v89, 0x3e0293ee, v140
	v_fmamk_f32 v90, v90, 0x3e0293ee, v140
	v_fmamk_f32 v91, v91, 0x3e0293ee, v140
	v_fmamk_f32 v92, v92, 0x3e0293ee, v140
	v_fmamk_f32 v94, v94, 0x3e0293ee, v140
	v_fmamk_f32 v95, v95, 0x3e0293ee, v140
	v_fmamk_f32 v96, v96, 0x3e0293ee, v140
	v_fmamk_f32 v97, v97, 0x3e0293ee, v140
	v_fmamk_f32 v98, v98, 0x3e0293ee, v140
	v_fmamk_f32 v99, v99, 0x3e0293ee, v140
	v_fmamk_f32 v141, v68, 0x3e0293ee, v140
	v_fmamk_f32 v142, v69, 0x3e0293ee, v140
	v_fmamk_f32 v143, v70, 0x3e0293ee, v140
	v_fmamk_f32 v144, v71, 0x3e0293ee, v140
	v_fmamk_f32 v145, v72, 0x3e0293ee, v140
	v_fmamk_f32 v146, v73, 0x3e0293ee, v140
	v_fmamk_f32 v147, v74, 0x3e0293ee, v140
	v_fmamk_f32 v166, v75, 0x3e0293ee, v140
	v_fmamk_f32 v203, v76, 0x3e0293ee, v140
	v_fmamk_f32 v204, v77, 0x3e0293ee, v140
	v_fmamk_f32 v205, v78, 0x3e0293ee, v140
	v_fmamk_f32 v206, v79, 0x3e0293ee, v140
	v_fmamk_f32 v207, v80, 0x3e0293ee, v140
	v_fmamk_f32 v208, v81, 0x3e0293ee, v140
	v_fmamk_f32 v209, v82, 0x3e0293ee, v140
	v_fmac_f32_e32 v140, 0x3e0293ee, v83
	v_exp_f32_e32 v210, v84
	v_exp_f32_e32 v211, v85
	v_exp_f32_e32 v212, v86
	v_exp_f32_e32 v213, v87
	v_exp_f32_e32 v214, v88
	v_exp_f32_e32 v215, v89
	v_exp_f32_e32 v216, v90
	v_exp_f32_e32 v217, v91
	v_exp_f32_e32 v218, v92
	v_exp_f32_e32 v222, v94
	v_exp_f32_e32 v223, v95
	v_exp_f32_e32 v224, v96
	v_exp_f32_e32 v225, v97
	v_exp_f32_e32 v226, v98
	v_exp_f32_e32 v227, v99
	s_barrier
	s_setprio 1
	v_add_u32_e32 v254, s95, v189
	ds_read_b128 v[68:71], v254 offset:49152
	ds_read_b128 v[72:75], v254 offset:49280
	v_add_u32_e32 v254, s95, v190
	ds_read_b128 v[76:79], v254 offset:49152
	ds_read_b128 v[80:83], v254 offset:49280
	v_add_u32_e32 v254, s95, v191
	ds_read_b128 v[228:231], v254 offset:49152
	ds_read_b128 v[232:235], v254 offset:49280
	v_add_u32_e32 v254, s95, v192
	ds_read_b128 v[236:239], v254 offset:49152
	ds_read_b128 v[240:243], v254 offset:49280
	v_add_u32_e32 v254, s95, v189
	ds_read_b128 v[246:249], v254 offset:57344
	ds_read_b128 v[250:253], v254 offset:57472
	s_waitcnt lgkmcnt(9)
	v_mfma_f32_32x32x16_bf16 v[84:99], v[68:71], v[100:103], 0
	s_waitcnt lgkmcnt(8)
	v_mfma_f32_32x32x16_bf16 v[84:99], v[72:75], v[116:119], v[84:99]
	s_waitcnt lgkmcnt(7)
	v_mfma_f32_32x32x16_bf16 v[84:99], v[76:79], v[104:107], v[84:99]
	s_waitcnt lgkmcnt(6)
	v_mfma_f32_32x32x16_bf16 v[84:99], v[80:83], v[120:123], v[84:99]
	s_waitcnt lgkmcnt(5)
	v_mfma_f32_32x32x16_bf16 v[84:99], v[228:231], v[108:111], v[84:99]
	v_add_u32_e32 v254, s95, v190
	ds_read_b128 v[228:231], v254 offset:57344
	s_waitcnt lgkmcnt(5)
	v_mfma_f32_32x32x16_bf16 v[84:99], v[232:235], v[124:127], v[84:99]
	ds_read_b128 v[232:235], v254 offset:57472
	s_waitcnt lgkmcnt(5)
	v_mfma_f32_32x32x16_bf16 v[84:99], v[236:239], v[112:115], v[84:99]
	v_add_u32_e32 v254, s95, v191
	ds_read_b128 v[236:239], v254 offset:57344
	s_waitcnt lgkmcnt(5)
	v_mfma_f32_32x32x16_bf16 v[84:99], v[240:243], v[128:131], v[84:99]
	ds_read_b128 v[240:243], v254 offset:57472
	s_waitcnt lgkmcnt(5)
	v_mfma_f32_32x32x16_bf16 v[68:83], v[246:249], v[100:103], 0
	v_add_u32_e32 v254, s95, v192
	ds_read_b128 v[246:249], v254 offset:57344
	s_waitcnt lgkmcnt(5)
	v_mfma_f32_32x32x16_bf16 v[68:83], v[250:253], v[116:119], v[68:83]
	ds_read_b128 v[250:253], v254 offset:57472
	s_waitcnt lgkmcnt(5)
	v_mfma_f32_32x32x16_bf16 v[68:83], v[228:231], v[104:107], v[68:83]
	s_waitcnt lgkmcnt(4)
	v_mfma_f32_32x32x16_bf16 v[68:83], v[232:235], v[120:123], v[68:83]
	s_waitcnt lgkmcnt(3)
	v_mfma_f32_32x32x16_bf16 v[68:83], v[236:239], v[108:111], v[68:83]
	s_waitcnt lgkmcnt(2)
	v_mfma_f32_32x32x16_bf16 v[68:83], v[240:243], v[124:127], v[68:83]
	s_waitcnt lgkmcnt(1)
	v_mfma_f32_32x32x16_bf16 v[68:83], v[246:249], v[112:115], v[68:83]
	s_waitcnt lgkmcnt(0)
	v_mfma_f32_32x32x16_bf16 v[68:83], v[250:253], v[128:131], v[68:83]
	s_barrier
	s_setprio 0
	v_exp_f32_e32 v140, v140
	v_exp_f32_e32 v139, v166
	v_add_f32_e32 v166, 0, v210
	v_add_f32_e32 v166, v211, v166
	v_add_f32_e32 v166, v212, v166
	v_add_f32_e32 v166, v213, v166
	v_add_f32_e32 v166, v214, v166
	v_add_f32_e32 v166, v215, v166
	v_add_f32_e32 v166, v216, v166
	v_add_f32_e32 v166, v217, v166
	v_add_f32_e32 v166, v218, v166
	v_add_f32_e32 v166, v221, v166
	v_add_f32_e32 v166, v222, v166
	v_add_f32_e32 v166, v223, v166
	v_exp_f32_e32 v132, v141
	v_add_f32_e32 v166, v224, v166
	v_exp_f32_e32 v133, v142
	v_add_f32_e32 v166, v225, v166
	v_exp_f32_e32 v134, v143
	v_add_f32_e32 v166, v226, v166
	v_exp_f32_e32 v135, v144
	v_add_f32_e32 v166, v227, v166
	v_exp_f32_e32 v136, v145
	v_add_f32_e32 v166, v132, v166
	v_exp_f32_e32 v137, v146
	v_add_f32_e32 v166, v133, v166
	v_exp_f32_e32 v138, v147
	v_add_f32_e32 v166, v134, v166
	v_add_f32_e32 v166, v135, v166
	v_exp_f32_e32 v141, v203
	v_add_f32_e32 v166, v136, v166
	v_exp_f32_e32 v142, v204
	v_add_f32_e32 v166, v137, v166
	v_exp_f32_e32 v143, v205
	v_add_f32_e32 v166, v138, v166
	v_exp_f32_e32 v144, v206
	v_add_f32_e32 v166, v139, v166
	v_exp_f32_e32 v145, v207
	v_add_f32_e32 v166, v141, v166
	v_exp_f32_e32 v146, v208
	v_add_f32_e32 v166, v142, v166
	v_exp_f32_e32 v147, v209
	v_add_f32_e32 v166, v143, v166
	v_add_f32_e32 v166, v144, v166
	v_add_f32_e32 v166, v145, v166
	v_add_f32_e32 v166, v146, v166
	v_add_f32_e32 v166, v147, v166
	v_add_f32_e32 v219, v140, v166
; __device__ __forceinline__ void finishSM(f32x16& p0, f32x16& p1, float alpha, float& l_reg, bf16x8& pa0, bf16x8& pa1, bf16x8& pa2, bf16x8& pa3) {
;     ...
;   { auto rr = __builtin_amdgcn_permlane32_swap(__float_as_uint(ps), __float_as_uint(ps), false, false);
;     ps = __uint_as_float(rr[0]) + __uint_as_float(rr[1]); }
;   l_reg = l_reg * alpha + ps;
;     ...
;   PK4(p0, 0, pa0); PK4(p0, 8, pa1); PK4(p1, 0, pa2); PK4(p1, 8, pa3);
;     ...
; }
; __device__ __forceinline__ void qkt(f32x16& p0, f32x16& p1, const u16* Ks, const bf16x8* qr, int r32, int hi) {
;   p0 = f32x16{}; p1 = f32x16{};
;   for (int d0 = 0; d0 < 8; ++d0) { int cb = (d0 * 16 + hi * 8) * 2;
;     bf16x8 b0 = *reinterpret_cast<const bf16x8*>((const char*)Ks + KSWZ(r32, cb));
;     bf16x8 b1 = *reinterpret_cast<const bf16x8*>((const char*)Ks + KSWZ(32 + r32, cb));
;     p0 = __builtin_amdgcn_mfma_f32_32x32x16_bf16(b0, qr[d0], p0, 0, 0, 0);
;     p1 = __builtin_amdgcn_mfma_f32_32x32x16_bf16(b1, qr[d0], p1, 0, 0, 0); }
; }
; __device__ __forceinline__ void qkt_lds(f32x16& p0, f32x16& p1, const u16* Ks, const char* qs, int r32, int hi) {
;   p0 = f32x16{}; p1 = f32x16{};
;   for (int d0 = 0; d0 < 8; ++d0) { int cb = (d0 * 16 + hi * 8) * 2;
;     bf16x8 q = *reinterpret_cast<const bf16x8*>(qs + d0 * 1024);
;     bf16x8 b0 = *reinterpret_cast<const bf16x8*>((const char*)Ks + KSWZ(r32, cb));
;     bf16x8 b1 = *reinterpret_cast<const bf16x8*>((const char*)Ks + KSWZ(32 + r32, cb));
;     p0 = __builtin_amdgcn_mfma_f32_32x32x16_bf16(b0, q, p0, 0, 0, 0);
;     p1 = __builtin_amdgcn_mfma_f32_32x32x16_bf16(b1, q, p1, 0, 0, 0); }
; }
; __device__ __forceinline__ int v_st(int k, int c) { const int kk = (k & ~0xC) | ((k & 4) << 1) | ((k & 8) >> 1); return ((kk >> 3) * 4 + (c >> 5)) * 512 + ((kk & 7) * 32 + (c & 31)) * 2; }
; __device__ __forceinline__ int v_rd_base(int lane) { return ((lane & 3) << 3) | (((lane >> 2) & 3) << 6) | (((lane >> 4) & 1) << 5) | (((lane >> 5) & 1) << 8); }
; template <int OFF> __device__ __forceinline__ s16x4 tr_read(int vb) {
;   s16x4 r; asm volatile("ds_read_b64_tr_b16 %0, %1 offset:%2" : "=&v"(r) : "v"(vb), "i"(OFF) : "memory"); return r;
; }
; template <int D0> __device__ __forceinline__ void pv_one(f32x16& od, int vb, bf16x8 pa0, bf16x8 pa1, bf16x8 pa2, bf16x8 pa3) {
	v_mov_b32_e32 v220, v219
	s_nop 1
	v_permlane32_swap_b32_e32 v219, v220
	v_cvt_pk_bf16_f32 v204, v210, v211
	v_cvt_pk_bf16_f32 v205, v212, v213
	v_cvt_pk_bf16_f32 v206, v214, v215
	v_cvt_pk_bf16_f32 v207, v216, v217
	v_cvt_pk_bf16_f32 v208, v218, v221
	v_cvt_pk_bf16_f32 v209, v222, v223
	v_cvt_pk_bf16_f32 v210, v224, v225
	v_cvt_pk_bf16_f32 v211, v226, v227
	v_cvt_pk_bf16_f32 v212, v132, v133
	v_cvt_pk_bf16_f32 v213, v134, v135
	v_cvt_pk_bf16_f32 v214, v136, v137
	v_cvt_pk_bf16_f32 v215, v138, v139
	v_cvt_pk_bf16_f32 v222, v141, v142
	v_cvt_pk_bf16_f32 v223, v143, v144
	v_cvt_pk_bf16_f32 v224, v145, v146
	v_cvt_pk_bf16_f32 v225, v147, v140
	s_nop 0
	v_permlane32_swap_b32_e32 v204, v206
	v_permlane32_swap_b32_e32 v205, v207
	v_permlane32_swap_b32_e32 v208, v210
	v_permlane32_swap_b32_e32 v209, v211
	v_permlane32_swap_b32_e32 v212, v214
	v_permlane32_swap_b32_e32 v213, v215
	v_permlane32_swap_b32_e32 v222, v224
	v_permlane32_swap_b32_e32 v223, v225
	s_min_u32 s7, s16, s90
	s_add_i32 s7, s7, s88
	s_lshl_b32 s7, s7, 6
	v_add_u32_e32 v244, s7, v167
	v_add_u32_e32 v245, s7, v185
	v_lshl_or_b32 v244, v244, 8, v182
	v_lshl_or_b32 v245, v245, 8, v182
	global_load_dwordx4 v[136:139], v244, s[58:59]
	global_load_dwordx4 v[132:135], v245, s[58:59]
	global_load_dwordx4 v[144:147], v244, s[64:65]
	global_load_dwordx4 v[140:143], v245, s[64:65]
	v_add_u32_e32 v254, s93, v197
	ds_read_b64_tr_b16 v[230:231], v254 offset:0
	ds_read_b64_tr_b16 v[232:233], v254 offset:2048
	ds_read_b64_tr_b16 v[234:235], v254 offset:4096
	ds_read_b64_tr_b16 v[236:237], v254 offset:6144
	ds_read_b64_tr_b16 v[238:239], v254 offset:8192
	ds_read_b64_tr_b16 v[240:241], v254 offset:10240
	ds_read_b64_tr_b16 v[242:243], v254 offset:12288
	ds_read_b64_tr_b16 v[244:245], v254 offset:14336
	ds_read_b64_tr_b16 v[246:247], v254 offset:512
	ds_read_b64_tr_b16 v[248:249], v254 offset:2560
	s_barrier
	s_setprio 1
	s_waitcnt lgkmcnt(6)
	v_mfma_f32_32x32x16_bf16 v[52:67], v[204:207], v[230:233], v[52:67]
	ds_read_b64_tr_b16 v[250:251], v254 offset:4608
	ds_read_b64_tr_b16 v[252:253], v254 offset:6656
	v_mfma_f32_32x32x16_bf16 v[52:67], v[208:211], v[234:237], v[52:67]
	ds_read_b64_tr_b16 v[230:231], v254 offset:8704
	ds_read_b64_tr_b16 v[232:233], v254 offset:10752
	s_waitcnt lgkmcnt(6)
	v_mfma_f32_32x32x16_bf16 v[52:67], v[212:215], v[238:241], v[52:67]
	ds_read_b64_tr_b16 v[234:235], v254 offset:12800
	ds_read_b64_tr_b16 v[236:237], v254 offset:14848
	v_mfma_f32_32x32x16_bf16 v[52:67], v[222:225], v[242:245], v[52:67]
	ds_read_b64_tr_b16 v[238:239], v254 offset:1024
	ds_read_b64_tr_b16 v[240:241], v254 offset:3072
	s_waitcnt lgkmcnt(6)
	v_mfma_f32_32x32x16_bf16 v[36:51], v[204:207], v[246:249], v[36:51]
	ds_read_b64_tr_b16 v[242:243], v254 offset:5120
	ds_read_b64_tr_b16 v[244:245], v254 offset:7168
	v_mfma_f32_32x32x16_bf16 v[36:51], v[208:211], v[250:253], v[36:51]
	ds_read_b64_tr_b16 v[246:247], v254 offset:9216
	ds_read_b64_tr_b16 v[248:249], v254 offset:11264
	s_waitcnt lgkmcnt(6)
	v_mfma_f32_32x32x16_bf16 v[36:51], v[212:215], v[230:233], v[36:51]
	ds_read_b64_tr_b16 v[250:251], v254 offset:13312
	ds_read_b64_tr_b16 v[252:253], v254 offset:15360
	v_mfma_f32_32x32x16_bf16 v[36:51], v[222:225], v[234:237], v[36:51]
	ds_read_b64_tr_b16 v[230:231], v254 offset:1536
	ds_read_b64_tr_b16 v[232:233], v254 offset:3584
	s_waitcnt lgkmcnt(6)
	v_mfma_f32_32x32x16_bf16 v[20:35], v[204:207], v[238:241], v[20:35]
	ds_read_b64_tr_b16 v[234:235], v254 offset:5632
	ds_read_b64_tr_b16 v[236:237], v254 offset:7680
	v_mfma_f32_32x32x16_bf16 v[20:35], v[208:211], v[242:245], v[20:35]
	ds_read_b64_tr_b16 v[238:239], v254 offset:9728
	ds_read_b64_tr_b16 v[240:241], v254 offset:11776
	s_waitcnt lgkmcnt(6)
	v_mfma_f32_32x32x16_bf16 v[20:35], v[212:215], v[246:249], v[20:35]
	ds_read_b64_tr_b16 v[242:243], v254 offset:13824
	ds_read_b64_tr_b16 v[244:245], v254 offset:15872
	v_mfma_f32_32x32x16_bf16 v[20:35], v[222:225], v[250:253], v[20:35]
	s_waitcnt lgkmcnt(4)
	v_mfma_f32_32x32x16_bf16 v[4:19], v[204:207], v[230:233], v[4:19]
	v_mfma_f32_32x32x16_bf16 v[4:19], v[208:211], v[234:237], v[4:19]
	s_waitcnt lgkmcnt(0)
	v_mfma_f32_32x32x16_bf16 v[4:19], v[212:215], v[238:241], v[4:19]
	v_mfma_f32_32x32x16_bf16 v[4:19], v[222:225], v[242:245], v[4:19]
	s_setprio 0
	s_add_i32 s30, s94, 0
	v_add_u32_e32 v203, s30, v184
	s_waitcnt vmcnt(4)
	ds_write_b128 v203, v[152:155]
	v_add_u32_e32 v152, s30, v186
	ds_write_b128 v152, v[148:151]
	v_add_u32_e32 v148, s30, v187
	ds_write_b128 v148, v[160:163] offset:49152
	v_add_u32_e32 v148, s30, v188
	s_waitcnt vmcnt(4)
	ds_write_b128 v148, v[156:159] offset:49152
	s_waitcnt lgkmcnt(0)
	s_barrier
; __device__ __forceinline__ void partialSM(f32x16& p0, f32x16& p1, float& m_reg, float& mn, float& alpha) {
;   constexpr float C = SCALE * 1.4426950408889634f;
;   float pmax = p0[0]; for (int r = 1; r < 16; ++r) pmax = fmaxf(pmax, p0[r]); for (int r = 0; r < 16; ++r) pmax = fmaxf(pmax, p1[r]);
;   { auto rr = __builtin_amdgcn_permlane32_swap(__float_as_uint(pmax), __float_as_uint(pmax), false, false);
;     pmax = fmaxf(__uint_as_float(rr[0]), __uint_as_float(rr[1])); }
;   if (__builtin_expect(__all(pmax - m_reg <= THR / SCALE), 1)) { mn = m_reg; alpha = 1.f; }
;   else { mn = fmaxf(m_reg, pmax); alpha = __builtin_amdgcn_exp2f((m_reg - mn) * C); m_reg = mn; }
	v_max_f32_e32 v166, v85, v85
	v_max_f32_e32 v203, v84, v84
	v_max_f32_e32 v166, v203, v166
	v_max3_f32 v166, v166, v86, v87
	v_max3_f32 v166, v166, v88, v89
	v_max3_f32 v166, v166, v90, v91
	v_max3_f32 v166, v166, v92, v93
	v_max3_f32 v166, v166, v94, v95
	v_max3_f32 v166, v166, v96, v97
	v_max3_f32 v166, v166, v98, v99
	v_max3_f32 v166, v166, v68, v69
	v_max3_f32 v166, v166, v70, v71
	v_max3_f32 v166, v166, v72, v73
	v_max3_f32 v166, v166, v74, v75
	v_max3_f32 v166, v166, v76, v77
	v_max3_f32 v166, v166, v78, v79
	v_max3_f32 v166, v166, v80, v81
	v_max3_f32 v166, v166, v82, v83
	v_mov_b32_e32 v203, v166
	s_nop 1
	v_permlane32_swap_b32_e32 v166, v203
	v_max_f32_e32 v203, v203, v203
	v_max_f32_e32 v166, v166, v166
	v_max_f32_e32 v166, v166, v203
	v_sub_f32_e32 v203, v166, v2
	v_cmp_ge_f32_e32 vcc, s74, v203
	v_max_f32_e32 v203, v2, v2
	v_max_f32_e32 v166, v203, v166
	v_sub_f32_e32 v203, v2, v166
	v_mul_f32_e32 v203, 0x3e0293ee, v203
	v_exp_f32_e32 v203, v203
	s_cmp_eq_u64 vcc, exec
	s_cselect_b64 s[6:7], -1, 0
	v_cndmask_b32_e64 v221, v203, 1.0, s[6:7]
	v_cmp_gt_f32_e32 vcc, 1.0, v221
	s_cbranch_vccz .Lstg_r2
	s_and_saveexec_b64 s[66:67], s[4:5]
	ds_write_b32 v183, v221 offset:128
	s_or_b64 exec, exec, s[66:67]
	s_waitcnt lgkmcnt(0)
	v_add_u32_e32 v160, v181, v180
	ds_read_b128 v[148:151], v160 offset:224
	ds_read_b128 v[152:155], v160 offset:192
	ds_read_b128 v[156:159], v160 offset:160
	ds_read_b128 v[160:163], v160 offset:128
	s_waitcnt lgkmcnt(3)
	v_pk_mul_f32 v[64:65], v[64:65], v[148:149]
	s_waitcnt lgkmcnt(2)
	v_pk_mul_f32 v[60:61], v[60:61], v[152:153]
	s_waitcnt lgkmcnt(1)
	v_pk_mul_f32 v[56:57], v[56:57], v[156:157]
	v_pk_mul_f32 v[66:67], v[66:67], v[150:151]
	v_pk_mul_f32 v[62:63], v[62:63], v[154:155]
	v_pk_mul_f32 v[58:59], v[58:59], v[158:159]
	s_waitcnt lgkmcnt(0)
	v_pk_mul_f32 v[54:55], v[54:55], v[162:163]
	v_pk_mul_f32 v[52:53], v[52:53], v[160:161]
	v_pk_mul_f32 v[48:49], v[48:49], v[148:149]
	v_pk_mul_f32 v[44:45], v[44:45], v[152:153]
	v_pk_mul_f32 v[40:41], v[40:41], v[156:157]
	v_pk_mul_f32 v[50:51], v[50:51], v[150:151]
	v_pk_mul_f32 v[46:47], v[46:47], v[154:155]
	v_pk_mul_f32 v[42:43], v[42:43], v[158:159]
	v_pk_mul_f32 v[38:39], v[38:39], v[162:163]
	v_pk_mul_f32 v[36:37], v[36:37], v[160:161]
	v_pk_mul_f32 v[32:33], v[32:33], v[148:149]
	v_pk_mul_f32 v[28:29], v[28:29], v[152:153]
	v_pk_mul_f32 v[24:25], v[24:25], v[156:157]
	v_pk_mul_f32 v[34:35], v[34:35], v[150:151]
	v_pk_mul_f32 v[30:31], v[30:31], v[154:155]
	v_pk_mul_f32 v[26:27], v[26:27], v[158:159]
	v_pk_mul_f32 v[22:23], v[22:23], v[162:163]
	v_pk_mul_f32 v[20:21], v[20:21], v[160:161]
	v_pk_mul_f32 v[16:17], v[16:17], v[148:149]
	v_pk_mul_f32 v[12:13], v[12:13], v[152:153]
	v_pk_mul_f32 v[8:9], v[8:9], v[156:157]
	v_pk_mul_f32 v[18:19], v[18:19], v[150:151]
	v_pk_mul_f32 v[14:15], v[14:15], v[154:155]
	v_pk_mul_f32 v[10:11], v[10:11], v[158:159]
	v_pk_mul_f32 v[6:7], v[6:7], v[162:163]
	v_pk_mul_f32 v[4:5], v[4:5], v[160:161]
